# v106 with heavy (6-piece) load phases at equal priority from their start
# speedup vs baseline: 1.0013x; 1.0013x over previous
.LBB0_333:
	s_add_u32 s68, s56, s49
	s_addc_u32 s70, s57, 0
	s_add_u32 s64, s68, 0x100
	s_addc_u32 s65, s70, 0
	s_and_b64 s[62:63], s[60:61], exec
	s_cselect_b32 s65, s18, s65
	s_cselect_b32 s64, s19, s64
	s_add_u32 s49, s54, s49
	s_addc_u32 s62, s55, 0
	s_add_u32 s49, s49, 0x100
	s_addc_u32 s62, s62, 0
	s_add_i32 s80, 0, 0x10000
	s_and_b64 s[60:61], s[60:61], exec
	s_cselect_b32 s67, s33, s62
	s_cselect_b32 s66, s45, s49
	s_add_i32 s61, 0, 0x14000
	s_add_u32 s72, s68, 0x10080
	s_addc_u32 s73, s70, 0
	s_add_i32 s79, s80, s2
	s_add_i32 m0, s4, 0xc000
	s_add_i32 s82, s4, 0xe000
	s_add_i32 s76, s79, 0x2000
	s_add_u32 s70, s66, 0x10000
	v_add_u32_e32 v152, s80, v138
	v_add_u32_e32 v168, s61, v138
	s_addc_u32 s71, s67, 0
	s_add_i32 s78, s61, s2
	ds_read_b128 v[140:143], v152
	ds_read_b128 v[144:147], v152 offset:1024
	ds_read_b128 v[148:151], v152 offset:2048
	ds_read_b128 v[152:155], v152 offset:3072
	ds_read_b128 v[156:159], v168
	ds_read_b128 v[160:163], v168 offset:1024
	ds_read_b128 v[164:167], v168 offset:2048
	ds_read_b128 v[168:171], v168 offset:3072
	s_add_i32 s77, s78, 0x2000
	s_add_i32 s75, 0, 0x18000
	s_add_i32 s74, 0, 0x1c000
	s_add_u32 s62, s64, 0x10000
	s_addc_u32 s63, s65, 0
	s_add_i32 s68, s75, s2
	s_add_i32 s49, s68, 0x2000
	s_add_u32 s60, s66, 0x10080
	s_addc_u32 s61, s67, 0
	s_add_i32 s81, s74, s2
	s_add_i32 s80, s81, 0x2000
	v_lshl_add_u64 v[204:205], s[72:73], 0, v[136:137]
	ds_read_b128 v[172:175], v139
	ds_read_b128 v[176:179], v139 offset:1024
	ds_read_b128 v[180:183], v139 offset:2048
	ds_read_b128 v[184:187], v139 offset:3072
	ds_read_b128 v[188:191], v139 offset:4096
	ds_read_b128 v[192:195], v139 offset:5120
	ds_read_b128 v[196:199], v139 offset:6144
	ds_read_b128 v[214:217], v139 offset:7168
	s_setprio 1
	global_load_lds_dwordx4 v[204:205], off
	v_lshl_add_u64 v[204:205], s[72:73], 0, v[134:135]
	s_mov_b32 m0, s82
	s_nop 0
	global_load_lds_dwordx4 v[204:205], off
	s_waitcnt vmcnt(8)
	s_waitcnt lgkmcnt(0)
	s_barrier
	v_mfma_f32_16x16x32_bf16 v[128:131], v[140:143], v[172:175], v[128:131]
	v_mfma_f32_16x16x32_bf16 v[124:127], v[148:151], v[172:175], v[124:127]
	v_mfma_f32_16x16x32_bf16 v[120:123], v[140:143], v[180:183], v[120:123]
	v_mfma_f32_16x16x32_bf16 v[116:119], v[148:151], v[180:183], v[116:119]
	v_mfma_f32_16x16x32_bf16 v[104:107], v[140:143], v[188:191], v[104:107]
	v_mfma_f32_16x16x32_bf16 v[100:103], v[148:151], v[188:191], v[100:103]
	v_mfma_f32_16x16x32_bf16 v[86:89], v[140:143], v[196:199], v[86:89]
	v_mfma_f32_16x16x32_bf16 v[82:85], v[148:151], v[196:199], v[82:85]
	v_mfma_f32_16x16x32_bf16 v[128:131], v[144:147], v[176:179], v[128:131]
	v_mfma_f32_16x16x32_bf16 v[124:127], v[152:155], v[176:179], v[124:127]
	v_mfma_f32_16x16x32_bf16 v[120:123], v[144:147], v[184:187], v[120:123]
	v_mfma_f32_16x16x32_bf16 v[116:119], v[152:155], v[184:187], v[116:119]
	v_mfma_f32_16x16x32_bf16 v[104:107], v[144:147], v[192:195], v[104:107]
	v_mfma_f32_16x16x32_bf16 v[100:103], v[152:155], v[192:195], v[100:103]
	v_mfma_f32_16x16x32_bf16 v[86:89], v[144:147], v[214:217], v[86:89]
	v_mfma_f32_16x16x32_bf16 v[82:85], v[152:155], v[214:217], v[82:85]
	s_setprio 0
	s_setprio 1
	v_mfma_f32_16x16x32_bf16 v[112:115], v[156:159], v[172:175], v[112:115]
	v_mfma_f32_16x16x32_bf16 v[108:111], v[164:167], v[172:175], v[108:111]
	v_mfma_f32_16x16x32_bf16 v[94:97], v[156:159], v[180:183], v[94:97]
	v_mfma_f32_16x16x32_bf16 v[90:93], v[164:167], v[180:183], v[90:93]
	v_mfma_f32_16x16x32_bf16 v[78:81], v[156:159], v[188:191], v[78:81]
	v_mfma_f32_16x16x32_bf16 v[74:77], v[164:167], v[188:191], v[74:77]
	v_mfma_f32_16x16x32_bf16 v[70:73], v[156:159], v[196:199], v[70:73]
	v_mfma_f32_16x16x32_bf16 v[66:69], v[164:167], v[196:199], v[66:69]
	v_mfma_f32_16x16x32_bf16 v[112:115], v[160:163], v[176:179], v[112:115]
	v_mfma_f32_16x16x32_bf16 v[108:111], v[168:171], v[176:179], v[108:111]
	v_mfma_f32_16x16x32_bf16 v[94:97], v[160:163], v[184:187], v[94:97]
	v_mfma_f32_16x16x32_bf16 v[90:93], v[168:171], v[184:187], v[90:93]
	v_mfma_f32_16x16x32_bf16 v[78:81], v[160:163], v[192:195], v[78:81]
	v_mfma_f32_16x16x32_bf16 v[74:77], v[168:171], v[192:195], v[74:77]
	v_mfma_f32_16x16x32_bf16 v[70:73], v[160:163], v[214:217], v[70:73]
	v_mfma_f32_16x16x32_bf16 v[66:69], v[168:171], v[214:217], v[66:69]
	s_barrier
	s_mov_b32 m0, s79
	v_lshl_add_u64 v[204:205], s[66:67], 0, v[98:99]
	ds_read_b128 v[172:175], v139 offset:16384
	ds_read_b128 v[176:179], v139 offset:17408
	ds_read_b128 v[180:183], v139 offset:18432
	ds_read_b128 v[184:187], v139 offset:19456
	ds_read_b128 v[188:191], v139 offset:20480
	ds_read_b128 v[192:195], v139 offset:21504
	ds_read_b128 v[196:199], v139 offset:22528
	ds_read_b128 v[214:217], v139 offset:23552
	global_load_lds_dwordx4 v[204:205], off
	v_lshl_add_u64 v[206:207], s[66:67], 0, v[132:133]
	s_mov_b32 m0, s76
	v_lshl_add_u64 v[208:209], s[70:71], 0, v[98:99]
	global_load_lds_dwordx4 v[206:207], off
	s_mov_b32 m0, s78
	v_lshl_add_u64 v[210:211], s[64:65], 0, v[134:135]
	global_load_lds_dwordx4 v[208:209], off
	v_lshl_add_u64 v[208:209], s[70:71], 0, v[132:133]
	s_mov_b32 m0, s77
	s_nop 0
	global_load_lds_dwordx4 v[208:209], off
	v_lshl_add_u64 v[208:209], s[64:65], 0, v[136:137]
	s_mov_b32 m0, s4
	s_nop 0
	global_load_lds_dwordx4 v[208:209], off
	s_mov_b32 m0, s7
	s_nop 0
	global_load_lds_dwordx4 v[210:211], off
	s_waitcnt vmcnt(8)
	s_waitcnt lgkmcnt(0)
	s_barrier
	v_mfma_f32_16x16x32_bf16 v[62:65], v[140:143], v[172:175], v[62:65]
	v_mfma_f32_16x16x32_bf16 v[58:61], v[148:151], v[172:175], v[58:61]
	v_mfma_f32_16x16x32_bf16 v[54:57], v[140:143], v[180:183], v[54:57]
	v_mfma_f32_16x16x32_bf16 v[50:53], v[148:151], v[180:183], v[50:53]
	v_mfma_f32_16x16x32_bf16 v[38:41], v[140:143], v[188:191], v[38:41]
	v_mfma_f32_16x16x32_bf16 v[34:37], v[148:151], v[188:191], v[34:37]
	v_mfma_f32_16x16x32_bf16 v[22:25], v[140:143], v[196:199], v[22:25]
	v_mfma_f32_16x16x32_bf16 v[18:21], v[148:151], v[196:199], v[18:21]
	v_mfma_f32_16x16x32_bf16 v[62:65], v[144:147], v[176:179], v[62:65]
	v_mfma_f32_16x16x32_bf16 v[58:61], v[152:155], v[176:179], v[58:61]
	v_mfma_f32_16x16x32_bf16 v[54:57], v[144:147], v[184:187], v[54:57]
	v_mfma_f32_16x16x32_bf16 v[50:53], v[152:155], v[184:187], v[50:53]
	v_mfma_f32_16x16x32_bf16 v[38:41], v[144:147], v[192:195], v[38:41]
	v_mfma_f32_16x16x32_bf16 v[34:37], v[152:155], v[192:195], v[34:37]
	v_mfma_f32_16x16x32_bf16 v[22:25], v[144:147], v[214:217], v[22:25]
	v_mfma_f32_16x16x32_bf16 v[18:21], v[152:155], v[214:217], v[18:21]
	s_setprio 0
	s_setprio 1
	v_mfma_f32_16x16x32_bf16 v[46:49], v[156:159], v[172:175], v[46:49]
	v_mfma_f32_16x16x32_bf16 v[42:45], v[164:167], v[172:175], v[42:45]
	v_mfma_f32_16x16x32_bf16 v[30:33], v[156:159], v[180:183], v[30:33]
	v_mfma_f32_16x16x32_bf16 v[26:29], v[164:167], v[180:183], v[26:29]
	v_mfma_f32_16x16x32_bf16 v[14:17], v[156:159], v[188:191], v[14:17]
	v_mfma_f32_16x16x32_bf16 v[10:13], v[164:167], v[188:191], v[10:13]
	v_mfma_f32_16x16x32_bf16 v[6:9], v[156:159], v[196:199], v[6:9]
	v_mfma_f32_16x16x32_bf16 v[2:5], v[164:167], v[196:199], v[2:5]
	v_mfma_f32_16x16x32_bf16 v[46:49], v[160:163], v[176:179], v[46:49]
	v_mfma_f32_16x16x32_bf16 v[42:45], v[168:171], v[176:179], v[42:45]
	v_mfma_f32_16x16x32_bf16 v[30:33], v[160:163], v[184:187], v[30:33]
	v_mfma_f32_16x16x32_bf16 v[26:29], v[168:171], v[184:187], v[26:29]
	v_mfma_f32_16x16x32_bf16 v[14:17], v[160:163], v[192:195], v[14:17]
	v_mfma_f32_16x16x32_bf16 v[10:13], v[168:171], v[192:195], v[10:13]
	v_mfma_f32_16x16x32_bf16 v[6:9], v[160:163], v[214:217], v[6:9]
	v_mfma_f32_16x16x32_bf16 v[2:5], v[168:171], v[214:217], v[2:5]
	s_setprio 0
	s_barrier
	v_add_u32_e32 v152, s75, v138
	v_add_u32_e32 v168, s74, v138
	ds_read_b128 v[140:143], v152
	ds_read_b128 v[144:147], v152 offset:1024
	ds_read_b128 v[148:151], v152 offset:2048
	ds_read_b128 v[152:155], v152 offset:3072
	ds_read_b128 v[156:159], v168
	ds_read_b128 v[160:163], v168 offset:1024
	ds_read_b128 v[164:167], v168 offset:2048
	ds_read_b128 v[168:171], v168 offset:3072
	s_mov_b32 m0, s8
	v_lshl_add_u64 v[218:219], s[62:63], 0, v[136:137]
	ds_read_b128 v[172:175], v139 offset:32768
	ds_read_b128 v[176:179], v139 offset:33792
	ds_read_b128 v[180:183], v139 offset:34816
	ds_read_b128 v[184:187], v139 offset:35840
	ds_read_b128 v[188:191], v139 offset:36864
	ds_read_b128 v[192:195], v139 offset:37888
	ds_read_b128 v[196:199], v139 offset:38912
	ds_read_b128 v[214:217], v139 offset:39936
	s_setprio 1
	global_load_lds_dwordx4 v[218:219], off
	v_lshl_add_u64 v[218:219], s[62:63], 0, v[134:135]
	s_mov_b32 m0, s9
	s_nop 0
	global_load_lds_dwordx4 v[218:219], off
	s_waitcnt vmcnt(8)
	s_waitcnt lgkmcnt(0)
	s_barrier
	v_mfma_f32_16x16x32_bf16 v[128:131], v[140:143], v[172:175], v[128:131]
	v_mfma_f32_16x16x32_bf16 v[124:127], v[148:151], v[172:175], v[124:127]
	v_mfma_f32_16x16x32_bf16 v[120:123], v[140:143], v[180:183], v[120:123]
	v_mfma_f32_16x16x32_bf16 v[116:119], v[148:151], v[180:183], v[116:119]
	v_mfma_f32_16x16x32_bf16 v[104:107], v[140:143], v[188:191], v[104:107]
	v_mfma_f32_16x16x32_bf16 v[100:103], v[148:151], v[188:191], v[100:103]
	v_mfma_f32_16x16x32_bf16 v[86:89], v[140:143], v[196:199], v[86:89]
	v_mfma_f32_16x16x32_bf16 v[82:85], v[148:151], v[196:199], v[82:85]
	v_mfma_f32_16x16x32_bf16 v[128:131], v[144:147], v[176:179], v[128:131]
	v_mfma_f32_16x16x32_bf16 v[124:127], v[152:155], v[176:179], v[124:127]
	v_mfma_f32_16x16x32_bf16 v[120:123], v[144:147], v[184:187], v[120:123]
	v_mfma_f32_16x16x32_bf16 v[116:119], v[152:155], v[184:187], v[116:119]
	v_mfma_f32_16x16x32_bf16 v[104:107], v[144:147], v[192:195], v[104:107]
	v_mfma_f32_16x16x32_bf16 v[100:103], v[152:155], v[192:195], v[100:103]
	v_mfma_f32_16x16x32_bf16 v[86:89], v[144:147], v[214:217], v[86:89]
	v_mfma_f32_16x16x32_bf16 v[82:85], v[152:155], v[214:217], v[82:85]
	s_setprio 0
	s_setprio 1
	v_mfma_f32_16x16x32_bf16 v[112:115], v[156:159], v[172:175], v[112:115]
	v_mfma_f32_16x16x32_bf16 v[108:111], v[164:167], v[172:175], v[108:111]
	v_mfma_f32_16x16x32_bf16 v[94:97], v[156:159], v[180:183], v[94:97]
	v_mfma_f32_16x16x32_bf16 v[90:93], v[164:167], v[180:183], v[90:93]
	v_mfma_f32_16x16x32_bf16 v[78:81], v[156:159], v[188:191], v[78:81]
	v_mfma_f32_16x16x32_bf16 v[74:77], v[164:167], v[188:191], v[74:77]
	v_mfma_f32_16x16x32_bf16 v[70:73], v[156:159], v[196:199], v[70:73]
	v_mfma_f32_16x16x32_bf16 v[66:69], v[164:167], v[196:199], v[66:69]
	v_mfma_f32_16x16x32_bf16 v[112:115], v[160:163], v[176:179], v[112:115]
	v_mfma_f32_16x16x32_bf16 v[108:111], v[168:171], v[176:179], v[108:111]
	v_mfma_f32_16x16x32_bf16 v[94:97], v[160:163], v[184:187], v[94:97]
	v_mfma_f32_16x16x32_bf16 v[90:93], v[168:171], v[184:187], v[90:93]
	v_mfma_f32_16x16x32_bf16 v[78:81], v[160:163], v[192:195], v[78:81]
	v_mfma_f32_16x16x32_bf16 v[74:77], v[168:171], v[192:195], v[74:77]
	v_mfma_f32_16x16x32_bf16 v[70:73], v[160:163], v[214:217], v[70:73]
	v_mfma_f32_16x16x32_bf16 v[66:69], v[168:171], v[214:217], v[66:69]
	s_barrier
	s_mov_b32 m0, s68
	v_lshl_add_u64 v[204:205], v[204:205], 0, s[28:29]
	ds_read_b128 v[172:175], v139 offset:49152
	ds_read_b128 v[176:179], v139 offset:50176
	ds_read_b128 v[180:183], v139 offset:51200
	ds_read_b128 v[184:187], v139 offset:52224
	ds_read_b128 v[188:191], v139 offset:53248
	ds_read_b128 v[192:195], v139 offset:54272
	ds_read_b128 v[196:199], v139 offset:55296
	ds_read_b128 v[214:217], v139 offset:56320
	global_load_lds_dwordx4 v[204:205], off
	v_lshl_add_u64 v[204:205], v[206:207], 0, s[28:29]
	s_mov_b32 m0, s49
	s_nop 0
	global_load_lds_dwordx4 v[204:205], off
	v_lshl_add_u64 v[204:205], s[60:61], 0, v[98:99]
	s_mov_b32 m0, s81
	s_nop 0
	global_load_lds_dwordx4 v[204:205], off
	v_lshl_add_u64 v[204:205], s[60:61], 0, v[132:133]
	s_mov_b32 m0, s80
	s_nop 0
	global_load_lds_dwordx4 v[204:205], off
	v_lshl_add_u64 v[204:205], v[208:209], 0, s[28:29]
	s_mov_b32 m0, s10
	s_nop 0
	global_load_lds_dwordx4 v[204:205], off
	v_lshl_add_u64 v[204:205], v[210:211], 0, s[28:29]
	s_mov_b32 m0, s11
	s_nop 0
	global_load_lds_dwordx4 v[204:205], off
	s_waitcnt vmcnt(8)
	s_waitcnt lgkmcnt(0)
	s_barrier
	v_mfma_f32_16x16x32_bf16 v[62:65], v[140:143], v[172:175], v[62:65]
	v_mfma_f32_16x16x32_bf16 v[58:61], v[148:151], v[172:175], v[58:61]
	v_mfma_f32_16x16x32_bf16 v[54:57], v[140:143], v[180:183], v[54:57]
	v_mfma_f32_16x16x32_bf16 v[50:53], v[148:151], v[180:183], v[50:53]
	v_mfma_f32_16x16x32_bf16 v[38:41], v[140:143], v[188:191], v[38:41]
	v_mfma_f32_16x16x32_bf16 v[34:37], v[148:151], v[188:191], v[34:37]
	v_mfma_f32_16x16x32_bf16 v[22:25], v[140:143], v[196:199], v[22:25]
	v_mfma_f32_16x16x32_bf16 v[18:21], v[148:151], v[196:199], v[18:21]
	v_mfma_f32_16x16x32_bf16 v[62:65], v[144:147], v[176:179], v[62:65]
	v_mfma_f32_16x16x32_bf16 v[58:61], v[152:155], v[176:179], v[58:61]
	v_mfma_f32_16x16x32_bf16 v[54:57], v[144:147], v[184:187], v[54:57]
	v_mfma_f32_16x16x32_bf16 v[50:53], v[152:155], v[184:187], v[50:53]
	v_mfma_f32_16x16x32_bf16 v[38:41], v[144:147], v[192:195], v[38:41]
	v_mfma_f32_16x16x32_bf16 v[34:37], v[152:155], v[192:195], v[34:37]
	v_mfma_f32_16x16x32_bf16 v[22:25], v[144:147], v[214:217], v[22:25]
	v_mfma_f32_16x16x32_bf16 v[18:21], v[152:155], v[214:217], v[18:21]
	s_setprio 0
	s_setprio 1
	v_mfma_f32_16x16x32_bf16 v[46:49], v[156:159], v[172:175], v[46:49]
	v_mfma_f32_16x16x32_bf16 v[42:45], v[164:167], v[172:175], v[42:45]
	v_mfma_f32_16x16x32_bf16 v[30:33], v[156:159], v[180:183], v[30:33]
	v_mfma_f32_16x16x32_bf16 v[26:29], v[164:167], v[180:183], v[26:29]
	v_mfma_f32_16x16x32_bf16 v[14:17], v[156:159], v[188:191], v[14:17]
	v_mfma_f32_16x16x32_bf16 v[10:13], v[164:167], v[188:191], v[10:13]
	v_mfma_f32_16x16x32_bf16 v[6:9], v[156:159], v[196:199], v[6:9]
	v_mfma_f32_16x16x32_bf16 v[2:5], v[164:167], v[196:199], v[2:5]
	v_mfma_f32_16x16x32_bf16 v[46:49], v[160:163], v[176:179], v[46:49]
	v_mfma_f32_16x16x32_bf16 v[42:45], v[168:171], v[176:179], v[42:45]
	v_mfma_f32_16x16x32_bf16 v[30:33], v[160:163], v[184:187], v[30:33]
	v_mfma_f32_16x16x32_bf16 v[26:29], v[168:171], v[184:187], v[26:29]
	v_mfma_f32_16x16x32_bf16 v[14:17], v[160:163], v[192:195], v[14:17]
	v_mfma_f32_16x16x32_bf16 v[10:13], v[168:171], v[192:195], v[10:13]
	v_mfma_f32_16x16x32_bf16 v[6:9], v[160:163], v[214:217], v[6:9]
	v_mfma_f32_16x16x32_bf16 v[2:5], v[168:171], v[214:217], v[2:5]
	s_setprio 0
	s_barrier
	s_movk_i32 s49, 0x100
	s_andn2_b64 vcc, exec, s[58:59]
	s_mov_b64 s[60:61], -1
	s_mov_b64 s[58:59], 0
	s_cbranch_vccz .LBB0_333
	s_and_b64 vcc, exec, s[40:41]
	s_cbranch_vccz .LBB0_336
	s_barrier

.LBB0_438:
	s_add_u32 s42, s40, 0xfffc0080
	s_addc_u32 s43, s41, -1
	s_add_i32 s67, 0, 0x10000
	s_cmp_eq_u32 s66, 12
	s_cselect_b32 s45, s1, s43
	s_cselect_b32 s44, s49, s42
	s_cselect_b32 s43, s55, s65
	s_cselect_b32 s42, s63, s64
	s_add_i32 s72, 0, 0x14000
	v_add_u32_e32 v108, s67, v162
	v_add_u32_e32 v160, s72, v162
	ds_read_b128 v[90:93], v108
	ds_read_b128 v[94:97], v108 offset:1024
	ds_read_b128 v[100:103], v108 offset:2048
	ds_read_b128 v[108:111], v108 offset:3072
	ds_read_b128 v[166:169], v160
	ds_read_b128 v[170:173], v160 offset:1024
	ds_read_b128 v[174:177], v160 offset:2048
	ds_read_b128 v[178:181], v160 offset:3072
	v_lshl_add_u64 v[160:161], s[40:41], 0, v[156:157]
	s_add_i32 m0, s8, 0xc000
	ds_read_b128 v[182:185], v163
	ds_read_b128 v[186:189], v163 offset:1024
	ds_read_b128 v[190:193], v163 offset:2048
	ds_read_b128 v[194:197], v163 offset:3072
	ds_read_b128 v[214:217], v163 offset:4096
	ds_read_b128 v[218:221], v163 offset:5120
	ds_read_b128 v[222:225], v163 offset:6144
	ds_read_b128 v[226:229], v163 offset:7168
	s_setprio 1
	global_load_lds_dwordx4 v[160:161], off
	v_lshl_add_u64 v[160:161], s[40:41], 0, v[158:159]
	s_add_i32 m0, s8, 0xe000
	s_nop 0
	global_load_lds_dwordx4 v[160:161], off
	s_waitcnt vmcnt(8)
	s_waitcnt lgkmcnt(0)
	s_barrier
	v_mfma_f32_16x16x32_bf16 v[144:147], v[90:93], v[182:185], v[144:147]
	v_mfma_f32_16x16x32_bf16 v[140:143], v[100:103], v[182:185], v[140:143]
	v_mfma_f32_16x16x32_bf16 v[128:131], v[90:93], v[190:193], v[128:131]
	v_mfma_f32_16x16x32_bf16 v[124:127], v[100:103], v[190:193], v[124:127]
	v_mfma_f32_16x16x32_bf16 v[112:115], v[90:93], v[214:217], v[112:115]
	v_mfma_f32_16x16x32_bf16 v[104:107], v[100:103], v[214:217], v[104:107]
	v_mfma_f32_16x16x32_bf16 v[78:81], v[90:93], v[222:225], v[78:81]
	v_mfma_f32_16x16x32_bf16 v[74:77], v[100:103], v[222:225], v[74:77]
	v_mfma_f32_16x16x32_bf16 v[144:147], v[94:97], v[186:189], v[144:147]
	v_mfma_f32_16x16x32_bf16 v[140:143], v[108:111], v[186:189], v[140:143]
	v_mfma_f32_16x16x32_bf16 v[128:131], v[94:97], v[194:197], v[128:131]
	v_mfma_f32_16x16x32_bf16 v[124:127], v[108:111], v[194:197], v[124:127]
	v_mfma_f32_16x16x32_bf16 v[112:115], v[94:97], v[218:221], v[112:115]
	v_mfma_f32_16x16x32_bf16 v[104:107], v[108:111], v[218:221], v[104:107]
	v_mfma_f32_16x16x32_bf16 v[78:81], v[94:97], v[226:229], v[78:81]
	v_mfma_f32_16x16x32_bf16 v[74:77], v[108:111], v[226:229], v[74:77]
	s_setprio 0
	s_setprio 1
	v_mfma_f32_16x16x32_bf16 v[136:139], v[166:169], v[182:185], v[136:139]
	v_mfma_f32_16x16x32_bf16 v[132:135], v[174:177], v[182:185], v[132:135]
	v_mfma_f32_16x16x32_bf16 v[120:123], v[166:169], v[190:193], v[120:123]
	v_mfma_f32_16x16x32_bf16 v[116:119], v[174:177], v[190:193], v[116:119]
	v_mfma_f32_16x16x32_bf16 v[86:89], v[166:169], v[214:217], v[86:89]
	v_mfma_f32_16x16x32_bf16 v[82:85], v[174:177], v[214:217], v[82:85]
	v_mfma_f32_16x16x32_bf16 v[70:73], v[166:169], v[222:225], v[70:73]
	v_mfma_f32_16x16x32_bf16 v[66:69], v[174:177], v[222:225], v[66:69]
	v_mfma_f32_16x16x32_bf16 v[136:139], v[170:173], v[186:189], v[136:139]
	v_mfma_f32_16x16x32_bf16 v[132:135], v[178:181], v[186:189], v[132:135]
	v_mfma_f32_16x16x32_bf16 v[120:123], v[170:173], v[194:197], v[120:123]
	v_mfma_f32_16x16x32_bf16 v[116:119], v[178:181], v[194:197], v[116:119]
	v_mfma_f32_16x16x32_bf16 v[86:89], v[170:173], v[218:221], v[86:89]
	v_mfma_f32_16x16x32_bf16 v[82:85], v[178:181], v[218:221], v[82:85]
	v_mfma_f32_16x16x32_bf16 v[70:73], v[170:173], v[226:229], v[70:73]
	v_mfma_f32_16x16x32_bf16 v[66:69], v[178:181], v[226:229], v[66:69]
	s_barrier
	s_add_i32 s67, s67, s7
	v_lshl_add_u64 v[160:161], s[42:43], 0, v[98:99]
	s_mov_b32 m0, s67
	ds_read_b128 v[182:185], v163 offset:16384
	ds_read_b128 v[186:189], v163 offset:17408
	ds_read_b128 v[190:193], v163 offset:18432
	ds_read_b128 v[194:197], v163 offset:19456
	ds_read_b128 v[214:217], v163 offset:20480
	ds_read_b128 v[218:221], v163 offset:21504
	ds_read_b128 v[222:225], v163 offset:22528
	ds_read_b128 v[226:229], v163 offset:23552
	global_load_lds_dwordx4 v[160:161], off
	s_add_i32 m0, s67, 0x2000
	s_add_u32 s70, s42, 0x40000
	v_lshl_add_u64 v[198:199], s[42:43], 0, v[152:153]
	s_addc_u32 s71, s43, 0
	s_add_i32 s67, s72, s7
	global_load_lds_dwordx4 v[198:199], off
	v_lshl_add_u64 v[204:205], s[70:71], 0, v[98:99]
	s_mov_b32 m0, s67
	v_lshl_add_u64 v[206:207], s[44:45], 0, v[150:151]
	global_load_lds_dwordx4 v[204:205], off
	v_lshl_add_u64 v[204:205], s[70:71], 0, v[152:153]
	s_add_i32 m0, s67, 0x2000
	s_nop 0
	global_load_lds_dwordx4 v[204:205], off
	v_lshl_add_u64 v[204:205], s[44:45], 0, v[148:149]
	s_mov_b32 m0, s8
	s_nop 0
	global_load_lds_dwordx4 v[204:205], off
	s_mov_b32 m0, s9
	s_nop 0
	global_load_lds_dwordx4 v[206:207], off
	s_waitcnt vmcnt(8)
	s_waitcnt lgkmcnt(0)
	s_barrier
	v_mfma_f32_16x16x32_bf16 v[62:65], v[90:93], v[182:185], v[62:65]
	v_mfma_f32_16x16x32_bf16 v[58:61], v[100:103], v[182:185], v[58:61]
	v_mfma_f32_16x16x32_bf16 v[46:49], v[90:93], v[190:193], v[46:49]
	v_mfma_f32_16x16x32_bf16 v[42:45], v[100:103], v[190:193], v[42:45]
	v_mfma_f32_16x16x32_bf16 v[30:33], v[90:93], v[214:217], v[30:33]
	v_mfma_f32_16x16x32_bf16 v[26:29], v[100:103], v[214:217], v[26:29]
	v_mfma_f32_16x16x32_bf16 v[14:17], v[90:93], v[222:225], v[14:17]
	v_mfma_f32_16x16x32_bf16 v[10:13], v[100:103], v[222:225], v[10:13]
	v_mfma_f32_16x16x32_bf16 v[62:65], v[94:97], v[186:189], v[62:65]
	v_mfma_f32_16x16x32_bf16 v[58:61], v[108:111], v[186:189], v[58:61]
	v_mfma_f32_16x16x32_bf16 v[46:49], v[94:97], v[194:197], v[46:49]
	v_mfma_f32_16x16x32_bf16 v[42:45], v[108:111], v[194:197], v[42:45]
	v_mfma_f32_16x16x32_bf16 v[30:33], v[94:97], v[218:221], v[30:33]
	v_mfma_f32_16x16x32_bf16 v[26:29], v[108:111], v[218:221], v[26:29]
	v_mfma_f32_16x16x32_bf16 v[14:17], v[94:97], v[226:229], v[14:17]
	v_mfma_f32_16x16x32_bf16 v[10:13], v[108:111], v[226:229], v[10:13]
	s_setprio 0
	s_setprio 1
	v_mfma_f32_16x16x32_bf16 v[54:57], v[166:169], v[182:185], v[54:57]
	v_mfma_f32_16x16x32_bf16 v[50:53], v[174:177], v[182:185], v[50:53]
	v_mfma_f32_16x16x32_bf16 v[38:41], v[166:169], v[190:193], v[38:41]
	v_mfma_f32_16x16x32_bf16 v[34:37], v[174:177], v[190:193], v[34:37]
	v_mfma_f32_16x16x32_bf16 v[22:25], v[166:169], v[214:217], v[22:25]
	v_mfma_f32_16x16x32_bf16 v[18:21], v[174:177], v[214:217], v[18:21]
	v_mfma_f32_16x16x32_bf16 v[6:9], v[166:169], v[222:225], v[6:9]
	v_mfma_f32_16x16x32_bf16 v[2:5], v[174:177], v[222:225], v[2:5]
	v_mfma_f32_16x16x32_bf16 v[54:57], v[170:173], v[186:189], v[54:57]
	v_mfma_f32_16x16x32_bf16 v[50:53], v[178:181], v[186:189], v[50:53]
	v_mfma_f32_16x16x32_bf16 v[38:41], v[170:173], v[194:197], v[38:41]
	v_mfma_f32_16x16x32_bf16 v[34:37], v[178:181], v[194:197], v[34:37]
	v_mfma_f32_16x16x32_bf16 v[22:25], v[170:173], v[218:221], v[22:25]
	v_mfma_f32_16x16x32_bf16 v[18:21], v[178:181], v[218:221], v[18:21]
	v_mfma_f32_16x16x32_bf16 v[6:9], v[170:173], v[226:229], v[6:9]
	v_mfma_f32_16x16x32_bf16 v[2:5], v[178:181], v[226:229], v[2:5]
	s_setprio 0
	s_barrier
	s_add_i32 s67, 0, 0x18000
	s_add_i32 s70, 0, 0x1c000
	v_add_u32_e32 v108, s67, v162
	v_add_u32_e32 v165, s70, v162
	ds_read_b128 v[90:93], v108
	ds_read_b128 v[94:97], v108 offset:1024
	ds_read_b128 v[100:103], v108 offset:2048
	ds_read_b128 v[108:111], v108 offset:3072
	ds_read_b128 v[166:169], v165
	ds_read_b128 v[170:173], v165 offset:1024
	ds_read_b128 v[174:177], v165 offset:2048
	ds_read_b128 v[178:181], v165 offset:3072
	s_add_u32 s44, s44, 0x40000
	s_addc_u32 s45, s45, 0
	s_mov_b32 m0, s10
	v_lshl_add_u64 v[208:209], s[44:45], 0, v[148:149]
	ds_read_b128 v[182:185], v163 offset:32768
	ds_read_b128 v[186:189], v163 offset:33792
	ds_read_b128 v[190:193], v163 offset:34816
	ds_read_b128 v[194:197], v163 offset:35840
	ds_read_b128 v[214:217], v163 offset:36864
	ds_read_b128 v[218:221], v163 offset:37888
	ds_read_b128 v[222:225], v163 offset:38912
	ds_read_b128 v[226:229], v163 offset:39936
	s_setprio 1
	global_load_lds_dwordx4 v[208:209], off
	v_lshl_add_u64 v[208:209], s[44:45], 0, v[150:151]
	s_mov_b32 m0, s11
	s_nop 0
	global_load_lds_dwordx4 v[208:209], off
	s_waitcnt vmcnt(8)
	s_waitcnt lgkmcnt(0)
	s_barrier
	v_mfma_f32_16x16x32_bf16 v[144:147], v[90:93], v[182:185], v[144:147]
	v_mfma_f32_16x16x32_bf16 v[140:143], v[100:103], v[182:185], v[140:143]
	v_mfma_f32_16x16x32_bf16 v[128:131], v[90:93], v[190:193], v[128:131]
	v_mfma_f32_16x16x32_bf16 v[124:127], v[100:103], v[190:193], v[124:127]
	v_mfma_f32_16x16x32_bf16 v[112:115], v[90:93], v[214:217], v[112:115]
	v_mfma_f32_16x16x32_bf16 v[104:107], v[100:103], v[214:217], v[104:107]
	v_mfma_f32_16x16x32_bf16 v[78:81], v[90:93], v[222:225], v[78:81]
	v_mfma_f32_16x16x32_bf16 v[74:77], v[100:103], v[222:225], v[74:77]
	v_mfma_f32_16x16x32_bf16 v[144:147], v[94:97], v[186:189], v[144:147]
	v_mfma_f32_16x16x32_bf16 v[140:143], v[108:111], v[186:189], v[140:143]
	v_mfma_f32_16x16x32_bf16 v[128:131], v[94:97], v[194:197], v[128:131]
	v_mfma_f32_16x16x32_bf16 v[124:127], v[108:111], v[194:197], v[124:127]
	v_mfma_f32_16x16x32_bf16 v[112:115], v[94:97], v[218:221], v[112:115]
	v_mfma_f32_16x16x32_bf16 v[104:107], v[108:111], v[218:221], v[104:107]
	v_mfma_f32_16x16x32_bf16 v[78:81], v[94:97], v[226:229], v[78:81]
	v_mfma_f32_16x16x32_bf16 v[74:77], v[108:111], v[226:229], v[74:77]
	s_setprio 0
	s_setprio 1
	v_mfma_f32_16x16x32_bf16 v[136:139], v[166:169], v[182:185], v[136:139]
	v_mfma_f32_16x16x32_bf16 v[132:135], v[174:177], v[182:185], v[132:135]
	v_mfma_f32_16x16x32_bf16 v[120:123], v[166:169], v[190:193], v[120:123]
	v_mfma_f32_16x16x32_bf16 v[116:119], v[174:177], v[190:193], v[116:119]
	v_mfma_f32_16x16x32_bf16 v[86:89], v[166:169], v[214:217], v[86:89]
	v_mfma_f32_16x16x32_bf16 v[82:85], v[174:177], v[214:217], v[82:85]
	v_mfma_f32_16x16x32_bf16 v[70:73], v[166:169], v[222:225], v[70:73]
	v_mfma_f32_16x16x32_bf16 v[66:69], v[174:177], v[222:225], v[66:69]
	v_mfma_f32_16x16x32_bf16 v[136:139], v[170:173], v[186:189], v[136:139]
	v_mfma_f32_16x16x32_bf16 v[132:135], v[178:181], v[186:189], v[132:135]
	v_mfma_f32_16x16x32_bf16 v[120:123], v[170:173], v[194:197], v[120:123]
	v_mfma_f32_16x16x32_bf16 v[116:119], v[178:181], v[194:197], v[116:119]
	v_mfma_f32_16x16x32_bf16 v[86:89], v[170:173], v[218:221], v[86:89]
	v_mfma_f32_16x16x32_bf16 v[82:85], v[178:181], v[218:221], v[82:85]
	v_mfma_f32_16x16x32_bf16 v[70:73], v[170:173], v[226:229], v[70:73]
	v_mfma_f32_16x16x32_bf16 v[66:69], v[178:181], v[226:229], v[66:69]
	s_barrier
	s_add_i32 s44, s67, s7
	v_lshl_add_u64 v[160:161], v[160:161], 0, s[28:29]
	s_mov_b32 m0, s44
	ds_read_b128 v[182:185], v163 offset:49152
	ds_read_b128 v[186:189], v163 offset:50176
	ds_read_b128 v[190:193], v163 offset:51200
	ds_read_b128 v[194:197], v163 offset:52224
	ds_read_b128 v[214:217], v163 offset:53248
	ds_read_b128 v[218:221], v163 offset:54272
	ds_read_b128 v[222:225], v163 offset:55296
	ds_read_b128 v[226:229], v163 offset:56320
	global_load_lds_dwordx4 v[160:161], off
	s_add_i32 m0, s44, 0x2000
	s_add_u32 s42, s42, 0x40080
	v_lshl_add_u64 v[160:161], v[198:199], 0, s[28:29]
	s_addc_u32 s43, s43, 0
	s_add_i32 s44, s70, s7
	global_load_lds_dwordx4 v[160:161], off
	v_lshl_add_u64 v[160:161], s[42:43], 0, v[98:99]
	s_mov_b32 m0, s44
	s_nop 0
	global_load_lds_dwordx4 v[160:161], off
	v_lshl_add_u64 v[160:161], s[42:43], 0, v[152:153]
	s_add_i32 m0, s44, 0x2000
	s_nop 0
	global_load_lds_dwordx4 v[160:161], off
	v_lshl_add_u64 v[160:161], v[204:205], 0, s[28:29]
	s_mov_b32 m0, s16
	s_nop 0
	global_load_lds_dwordx4 v[160:161], off
	v_lshl_add_u64 v[160:161], v[206:207], 0, s[28:29]
	s_mov_b32 m0, s17
	s_nop 0
	global_load_lds_dwordx4 v[160:161], off
	s_waitcnt vmcnt(8)
	s_waitcnt lgkmcnt(0)
	s_barrier
	v_mfma_f32_16x16x32_bf16 v[62:65], v[90:93], v[182:185], v[62:65]
	v_mfma_f32_16x16x32_bf16 v[58:61], v[100:103], v[182:185], v[58:61]
	v_mfma_f32_16x16x32_bf16 v[46:49], v[90:93], v[190:193], v[46:49]
	v_mfma_f32_16x16x32_bf16 v[42:45], v[100:103], v[190:193], v[42:45]
	v_mfma_f32_16x16x32_bf16 v[30:33], v[90:93], v[214:217], v[30:33]
	v_mfma_f32_16x16x32_bf16 v[26:29], v[100:103], v[214:217], v[26:29]
	v_mfma_f32_16x16x32_bf16 v[14:17], v[90:93], v[222:225], v[14:17]
	v_mfma_f32_16x16x32_bf16 v[10:13], v[100:103], v[222:225], v[10:13]
	v_mfma_f32_16x16x32_bf16 v[62:65], v[94:97], v[186:189], v[62:65]
	v_mfma_f32_16x16x32_bf16 v[58:61], v[108:111], v[186:189], v[58:61]
	v_mfma_f32_16x16x32_bf16 v[46:49], v[94:97], v[194:197], v[46:49]
	v_mfma_f32_16x16x32_bf16 v[42:45], v[108:111], v[194:197], v[42:45]
	v_mfma_f32_16x16x32_bf16 v[30:33], v[94:97], v[218:221], v[30:33]
	v_mfma_f32_16x16x32_bf16 v[26:29], v[108:111], v[218:221], v[26:29]
	v_mfma_f32_16x16x32_bf16 v[14:17], v[94:97], v[226:229], v[14:17]
	v_mfma_f32_16x16x32_bf16 v[10:13], v[108:111], v[226:229], v[10:13]
	s_setprio 0
	s_setprio 1
	v_mfma_f32_16x16x32_bf16 v[54:57], v[166:169], v[182:185], v[54:57]
	v_mfma_f32_16x16x32_bf16 v[50:53], v[174:177], v[182:185], v[50:53]
	v_mfma_f32_16x16x32_bf16 v[38:41], v[166:169], v[190:193], v[38:41]
	v_mfma_f32_16x16x32_bf16 v[34:37], v[174:177], v[190:193], v[34:37]
	v_mfma_f32_16x16x32_bf16 v[22:25], v[166:169], v[214:217], v[22:25]
	v_mfma_f32_16x16x32_bf16 v[18:21], v[174:177], v[214:217], v[18:21]
	v_mfma_f32_16x16x32_bf16 v[6:9], v[166:169], v[222:225], v[6:9]
	v_mfma_f32_16x16x32_bf16 v[2:5], v[174:177], v[222:225], v[2:5]
	v_mfma_f32_16x16x32_bf16 v[54:57], v[170:173], v[186:189], v[54:57]
	v_mfma_f32_16x16x32_bf16 v[50:53], v[178:181], v[186:189], v[50:53]
	v_mfma_f32_16x16x32_bf16 v[38:41], v[170:173], v[194:197], v[38:41]
	v_mfma_f32_16x16x32_bf16 v[34:37], v[178:181], v[194:197], v[34:37]
	v_mfma_f32_16x16x32_bf16 v[22:25], v[170:173], v[218:221], v[22:25]
	v_mfma_f32_16x16x32_bf16 v[18:21], v[178:181], v[218:221], v[18:21]
	v_mfma_f32_16x16x32_bf16 v[6:9], v[170:173], v[226:229], v[6:9]
	v_mfma_f32_16x16x32_bf16 v[2:5], v[178:181], v[226:229], v[2:5]
	s_setprio 0
	s_barrier
	s_add_i32 s66, s66, 2
	s_add_u32 s40, s40, 0x100
	s_addc_u32 s41, s41, 0
	s_add_u32 s64, s64, 0x100
	s_addc_u32 s65, s65, 0
	s_cmp_gt_u32 s66, 13
	s_cbranch_scc0 .LBB0_438
	s_and_b64 vcc, exec, s[22:23]
	s_cbranch_vccz .LBB0_441
	s_barrier

.LBB0_647:
	s_add_i32 s68, s42, 2
	s_add_u32 s43, s40, 0xfff80080
	s_addc_u32 s54, s41, -1
	s_add_i32 s70, 0, 0x10000
	s_cmp_eq_u32 s65, s42
	s_cselect_b32 s55, s49, s54
	s_cselect_b32 s54, s63, s43
	v_add_u32_e32 v146, s70, v149
	s_cselect_b32 s43, s51, s67
	s_cselect_b32 s42, s50, s66
	s_add_i32 s72, 0, 0x14000
	ds_read_b128 v[152:155], v146
	ds_read_b128 v[156:159], v146 offset:1024
	ds_read_b128 v[160:163], v146 offset:2048
	ds_read_b128 v[164:167], v146 offset:3072
	v_add_u32_e32 v146, s72, v149
	ds_read_b128 v[168:171], v146
	ds_read_b128 v[172:175], v146 offset:1024
	ds_read_b128 v[176:179], v146 offset:2048
	ds_read_b128 v[180:183], v146 offset:3072
	v_lshl_add_u64 v[146:147], s[40:41], 0, v[142:143]
	s_add_i32 m0, s11, 0xc000
	ds_read_b128 v[184:187], v150
	ds_read_b128 v[188:191], v150 offset:1024
	ds_read_b128 v[192:195], v150 offset:2048
	ds_read_b128 v[196:199], v150 offset:3072
	ds_read_b128 v[214:217], v150 offset:4096
	ds_read_b128 v[218:221], v150 offset:5120
	ds_read_b128 v[222:225], v150 offset:6144
	ds_read_b128 v[226:229], v150 offset:7168
	s_setprio 1
	global_load_lds_dwordx4 v[146:147], off
	v_lshl_add_u64 v[146:147], s[40:41], 0, v[144:145]
	s_add_i32 m0, s11, 0xe000
	s_nop 0
	global_load_lds_dwordx4 v[146:147], off
	s_waitcnt vmcnt(8)
	s_waitcnt lgkmcnt(0)
	s_barrier
	v_mfma_f32_16x16x32_bf16 v[128:131], v[152:155], v[184:187], v[128:131]
	v_mfma_f32_16x16x32_bf16 v[124:127], v[160:163], v[184:187], v[124:127]
	v_mfma_f32_16x16x32_bf16 v[112:115], v[152:155], v[192:195], v[112:115]
	v_mfma_f32_16x16x32_bf16 v[108:111], v[160:163], v[192:195], v[108:111]
	v_mfma_f32_16x16x32_bf16 v[94:97], v[152:155], v[214:217], v[94:97]
	v_mfma_f32_16x16x32_bf16 v[90:93], v[160:163], v[214:217], v[90:93]
	v_mfma_f32_16x16x32_bf16 v[78:81], v[152:155], v[222:225], v[78:81]
	v_mfma_f32_16x16x32_bf16 v[74:77], v[160:163], v[222:225], v[74:77]
	v_mfma_f32_16x16x32_bf16 v[128:131], v[156:159], v[188:191], v[128:131]
	v_mfma_f32_16x16x32_bf16 v[124:127], v[164:167], v[188:191], v[124:127]
	v_mfma_f32_16x16x32_bf16 v[112:115], v[156:159], v[196:199], v[112:115]
	v_mfma_f32_16x16x32_bf16 v[108:111], v[164:167], v[196:199], v[108:111]
	v_mfma_f32_16x16x32_bf16 v[94:97], v[156:159], v[218:221], v[94:97]
	v_mfma_f32_16x16x32_bf16 v[90:93], v[164:167], v[218:221], v[90:93]
	v_mfma_f32_16x16x32_bf16 v[78:81], v[156:159], v[226:229], v[78:81]
	v_mfma_f32_16x16x32_bf16 v[74:77], v[164:167], v[226:229], v[74:77]
	s_setprio 0
	s_setprio 1
	v_mfma_f32_16x16x32_bf16 v[120:123], v[168:171], v[184:187], v[120:123]
	v_mfma_f32_16x16x32_bf16 v[116:119], v[176:179], v[184:187], v[116:119]
	v_mfma_f32_16x16x32_bf16 v[104:107], v[168:171], v[192:195], v[104:107]
	v_mfma_f32_16x16x32_bf16 v[100:103], v[176:179], v[192:195], v[100:103]
	v_mfma_f32_16x16x32_bf16 v[86:89], v[168:171], v[214:217], v[86:89]
	v_mfma_f32_16x16x32_bf16 v[82:85], v[176:179], v[214:217], v[82:85]
	v_mfma_f32_16x16x32_bf16 v[70:73], v[168:171], v[222:225], v[70:73]
	v_mfma_f32_16x16x32_bf16 v[66:69], v[176:179], v[222:225], v[66:69]
	v_mfma_f32_16x16x32_bf16 v[120:123], v[172:175], v[188:191], v[120:123]
	v_mfma_f32_16x16x32_bf16 v[116:119], v[180:183], v[188:191], v[116:119]
	v_mfma_f32_16x16x32_bf16 v[104:107], v[172:175], v[196:199], v[104:107]
	v_mfma_f32_16x16x32_bf16 v[100:103], v[180:183], v[196:199], v[100:103]
	v_mfma_f32_16x16x32_bf16 v[86:89], v[172:175], v[218:221], v[86:89]
	v_mfma_f32_16x16x32_bf16 v[82:85], v[180:183], v[218:221], v[82:85]
	v_mfma_f32_16x16x32_bf16 v[70:73], v[172:175], v[226:229], v[70:73]
	v_mfma_f32_16x16x32_bf16 v[66:69], v[180:183], v[226:229], v[66:69]
	s_barrier
	s_add_i32 s70, s70, s10
	v_lshl_add_u64 v[146:147], s[42:43], 0, v[98:99]
	s_mov_b32 m0, s70
	ds_read_b128 v[184:187], v150 offset:16384
	ds_read_b128 v[188:191], v150 offset:17408
	ds_read_b128 v[192:195], v150 offset:18432
	ds_read_b128 v[196:199], v150 offset:19456
	ds_read_b128 v[214:217], v150 offset:20480
	ds_read_b128 v[218:221], v150 offset:21504
	ds_read_b128 v[222:225], v150 offset:22528
	ds_read_b128 v[226:229], v150 offset:23552
	global_load_lds_dwordx4 v[146:147], off
	s_add_i32 m0, s70, 0x2000
	s_add_u32 s70, s42, 0x18000
	v_lshl_add_u64 v[204:205], s[42:43], 0, v[136:137]
	s_addc_u32 s71, s43, 0
	s_add_i32 s72, s72, s10
	global_load_lds_dwordx4 v[204:205], off
	v_lshl_add_u64 v[206:207], s[70:71], 0, v[98:99]
	s_mov_b32 m0, s72
	v_lshl_add_u64 v[208:209], s[54:55], 0, v[134:135]
	global_load_lds_dwordx4 v[206:207], off
	v_lshl_add_u64 v[206:207], s[70:71], 0, v[136:137]
	s_add_i32 m0, s72, 0x2000
	s_nop 0
	global_load_lds_dwordx4 v[206:207], off
	v_lshl_add_u64 v[206:207], s[54:55], 0, v[132:133]
	s_mov_b32 m0, s11
	s_nop 0
	global_load_lds_dwordx4 v[206:207], off
	s_mov_b32 m0, s12
	s_nop 0
	global_load_lds_dwordx4 v[208:209], off
	s_waitcnt vmcnt(8)
	s_waitcnt lgkmcnt(0)
	s_barrier
	v_mfma_f32_16x16x32_bf16 v[62:65], v[152:155], v[184:187], v[62:65]
	v_mfma_f32_16x16x32_bf16 v[58:61], v[160:163], v[184:187], v[58:61]
	v_mfma_f32_16x16x32_bf16 v[46:49], v[152:155], v[192:195], v[46:49]
	v_mfma_f32_16x16x32_bf16 v[42:45], v[160:163], v[192:195], v[42:45]
	v_mfma_f32_16x16x32_bf16 v[30:33], v[152:155], v[214:217], v[30:33]
	v_mfma_f32_16x16x32_bf16 v[26:29], v[160:163], v[214:217], v[26:29]
	v_mfma_f32_16x16x32_bf16 v[14:17], v[152:155], v[222:225], v[14:17]
	v_mfma_f32_16x16x32_bf16 v[10:13], v[160:163], v[222:225], v[10:13]
	v_mfma_f32_16x16x32_bf16 v[62:65], v[156:159], v[188:191], v[62:65]
	v_mfma_f32_16x16x32_bf16 v[58:61], v[164:167], v[188:191], v[58:61]
	v_mfma_f32_16x16x32_bf16 v[46:49], v[156:159], v[196:199], v[46:49]
	v_mfma_f32_16x16x32_bf16 v[42:45], v[164:167], v[196:199], v[42:45]
	v_mfma_f32_16x16x32_bf16 v[30:33], v[156:159], v[218:221], v[30:33]
	v_mfma_f32_16x16x32_bf16 v[26:29], v[164:167], v[218:221], v[26:29]
	v_mfma_f32_16x16x32_bf16 v[14:17], v[156:159], v[226:229], v[14:17]
	v_mfma_f32_16x16x32_bf16 v[10:13], v[164:167], v[226:229], v[10:13]
	s_setprio 0
	s_setprio 1
	v_mfma_f32_16x16x32_bf16 v[54:57], v[168:171], v[184:187], v[54:57]
	v_mfma_f32_16x16x32_bf16 v[50:53], v[176:179], v[184:187], v[50:53]
	v_mfma_f32_16x16x32_bf16 v[38:41], v[168:171], v[192:195], v[38:41]
	v_mfma_f32_16x16x32_bf16 v[34:37], v[176:179], v[192:195], v[34:37]
	v_mfma_f32_16x16x32_bf16 v[22:25], v[168:171], v[214:217], v[22:25]
	v_mfma_f32_16x16x32_bf16 v[18:21], v[176:179], v[214:217], v[18:21]
	v_mfma_f32_16x16x32_bf16 v[6:9], v[168:171], v[222:225], v[6:9]
	v_mfma_f32_16x16x32_bf16 v[2:5], v[176:179], v[222:225], v[2:5]
	v_mfma_f32_16x16x32_bf16 v[54:57], v[172:175], v[188:191], v[54:57]
	v_mfma_f32_16x16x32_bf16 v[50:53], v[180:183], v[188:191], v[50:53]
	v_mfma_f32_16x16x32_bf16 v[38:41], v[172:175], v[196:199], v[38:41]
	v_mfma_f32_16x16x32_bf16 v[34:37], v[180:183], v[196:199], v[34:37]
	v_mfma_f32_16x16x32_bf16 v[22:25], v[172:175], v[218:221], v[22:25]
	v_mfma_f32_16x16x32_bf16 v[18:21], v[180:183], v[218:221], v[18:21]
	v_mfma_f32_16x16x32_bf16 v[6:9], v[172:175], v[226:229], v[6:9]
	v_mfma_f32_16x16x32_bf16 v[2:5], v[180:183], v[226:229], v[2:5]
	s_setprio 0
	s_barrier
	s_add_i32 s70, 0, 0x18000
	v_add_u32_e32 v151, s70, v149
	s_add_i32 s71, 0, 0x1c000
	ds_read_b128 v[152:155], v151
	ds_read_b128 v[156:159], v151 offset:1024
	ds_read_b128 v[160:163], v151 offset:2048
	ds_read_b128 v[164:167], v151 offset:3072
	v_add_u32_e32 v151, s71, v149
	ds_read_b128 v[168:171], v151
	ds_read_b128 v[172:175], v151 offset:1024
	ds_read_b128 v[176:179], v151 offset:2048
	ds_read_b128 v[180:183], v151 offset:3072
	s_add_u32 s54, s54, 0x80000
	s_addc_u32 s55, s55, 0
	s_mov_b32 m0, s13
	v_lshl_add_u64 v[210:211], s[54:55], 0, v[132:133]
	ds_read_b128 v[184:187], v150 offset:32768
	ds_read_b128 v[188:191], v150 offset:33792
	ds_read_b128 v[192:195], v150 offset:34816
	ds_read_b128 v[196:199], v150 offset:35840
	ds_read_b128 v[214:217], v150 offset:36864
	ds_read_b128 v[218:221], v150 offset:37888
	ds_read_b128 v[222:225], v150 offset:38912
	ds_read_b128 v[226:229], v150 offset:39936
	s_setprio 1
	global_load_lds_dwordx4 v[210:211], off
	v_lshl_add_u64 v[210:211], s[54:55], 0, v[134:135]
	s_mov_b32 m0, s14
	s_nop 0
	global_load_lds_dwordx4 v[210:211], off
	s_waitcnt vmcnt(8)
	s_waitcnt lgkmcnt(0)
	s_barrier
	v_mfma_f32_16x16x32_bf16 v[128:131], v[152:155], v[184:187], v[128:131]
	v_mfma_f32_16x16x32_bf16 v[124:127], v[160:163], v[184:187], v[124:127]
	v_mfma_f32_16x16x32_bf16 v[112:115], v[152:155], v[192:195], v[112:115]
	v_mfma_f32_16x16x32_bf16 v[108:111], v[160:163], v[192:195], v[108:111]
	v_mfma_f32_16x16x32_bf16 v[94:97], v[152:155], v[214:217], v[94:97]
	v_mfma_f32_16x16x32_bf16 v[90:93], v[160:163], v[214:217], v[90:93]
	v_mfma_f32_16x16x32_bf16 v[78:81], v[152:155], v[222:225], v[78:81]
	v_mfma_f32_16x16x32_bf16 v[74:77], v[160:163], v[222:225], v[74:77]
	v_mfma_f32_16x16x32_bf16 v[128:131], v[156:159], v[188:191], v[128:131]
	v_mfma_f32_16x16x32_bf16 v[124:127], v[164:167], v[188:191], v[124:127]
	v_mfma_f32_16x16x32_bf16 v[112:115], v[156:159], v[196:199], v[112:115]
	v_mfma_f32_16x16x32_bf16 v[108:111], v[164:167], v[196:199], v[108:111]
	v_mfma_f32_16x16x32_bf16 v[94:97], v[156:159], v[218:221], v[94:97]
	v_mfma_f32_16x16x32_bf16 v[90:93], v[164:167], v[218:221], v[90:93]
	v_mfma_f32_16x16x32_bf16 v[78:81], v[156:159], v[226:229], v[78:81]
	v_mfma_f32_16x16x32_bf16 v[74:77], v[164:167], v[226:229], v[74:77]
	s_setprio 0
	s_setprio 1
	v_mfma_f32_16x16x32_bf16 v[120:123], v[168:171], v[184:187], v[120:123]
	v_mfma_f32_16x16x32_bf16 v[116:119], v[176:179], v[184:187], v[116:119]
	v_mfma_f32_16x16x32_bf16 v[104:107], v[168:171], v[192:195], v[104:107]
	v_mfma_f32_16x16x32_bf16 v[100:103], v[176:179], v[192:195], v[100:103]
	v_mfma_f32_16x16x32_bf16 v[86:89], v[168:171], v[214:217], v[86:89]
	v_mfma_f32_16x16x32_bf16 v[82:85], v[176:179], v[214:217], v[82:85]
	v_mfma_f32_16x16x32_bf16 v[70:73], v[168:171], v[222:225], v[70:73]
	v_mfma_f32_16x16x32_bf16 v[66:69], v[176:179], v[222:225], v[66:69]
	v_mfma_f32_16x16x32_bf16 v[120:123], v[172:175], v[188:191], v[120:123]
	v_mfma_f32_16x16x32_bf16 v[116:119], v[180:183], v[188:191], v[116:119]
	v_mfma_f32_16x16x32_bf16 v[104:107], v[172:175], v[196:199], v[104:107]
	v_mfma_f32_16x16x32_bf16 v[100:103], v[180:183], v[196:199], v[100:103]
	v_mfma_f32_16x16x32_bf16 v[86:89], v[172:175], v[218:221], v[86:89]
	v_mfma_f32_16x16x32_bf16 v[82:85], v[180:183], v[218:221], v[82:85]
	v_mfma_f32_16x16x32_bf16 v[70:73], v[172:175], v[226:229], v[70:73]
	v_mfma_f32_16x16x32_bf16 v[66:69], v[180:183], v[226:229], v[66:69]
	s_barrier
	s_add_i32 s54, s70, s10
	v_lshl_add_u64 v[146:147], v[146:147], 0, s[28:29]
	s_mov_b32 m0, s54
	ds_read_b128 v[184:187], v150 offset:49152
	ds_read_b128 v[188:191], v150 offset:50176
	ds_read_b128 v[192:195], v150 offset:51200
	ds_read_b128 v[196:199], v150 offset:52224
	ds_read_b128 v[214:217], v150 offset:53248
	ds_read_b128 v[218:221], v150 offset:54272
	ds_read_b128 v[222:225], v150 offset:55296
	ds_read_b128 v[226:229], v150 offset:56320
	global_load_lds_dwordx4 v[146:147], off
	s_add_i32 m0, s54, 0x2000
	s_add_u32 s42, s42, 0x18080
	v_lshl_add_u64 v[146:147], v[204:205], 0, s[28:29]
	s_addc_u32 s43, s43, 0
	s_add_i32 s54, s71, s10
	global_load_lds_dwordx4 v[146:147], off
	v_lshl_add_u64 v[146:147], s[42:43], 0, v[98:99]
	s_mov_b32 m0, s54
	s_nop 0
	global_load_lds_dwordx4 v[146:147], off
	v_lshl_add_u64 v[146:147], s[42:43], 0, v[136:137]
	s_add_i32 m0, s54, 0x2000
	s_nop 0
	global_load_lds_dwordx4 v[146:147], off
	v_lshl_add_u64 v[146:147], v[206:207], 0, s[28:29]
	s_mov_b32 m0, s17
	s_nop 0
	global_load_lds_dwordx4 v[146:147], off
	v_lshl_add_u64 v[146:147], v[208:209], 0, s[28:29]
	s_mov_b32 m0, s18
	s_nop 0
	global_load_lds_dwordx4 v[146:147], off
	s_waitcnt vmcnt(8)
	s_waitcnt lgkmcnt(0)
	s_barrier
	v_mfma_f32_16x16x32_bf16 v[62:65], v[152:155], v[184:187], v[62:65]
	v_mfma_f32_16x16x32_bf16 v[58:61], v[160:163], v[184:187], v[58:61]
	v_mfma_f32_16x16x32_bf16 v[46:49], v[152:155], v[192:195], v[46:49]
	v_mfma_f32_16x16x32_bf16 v[42:45], v[160:163], v[192:195], v[42:45]
	v_mfma_f32_16x16x32_bf16 v[30:33], v[152:155], v[214:217], v[30:33]
	v_mfma_f32_16x16x32_bf16 v[26:29], v[160:163], v[214:217], v[26:29]
	v_mfma_f32_16x16x32_bf16 v[14:17], v[152:155], v[222:225], v[14:17]
	v_mfma_f32_16x16x32_bf16 v[10:13], v[160:163], v[222:225], v[10:13]
	v_mfma_f32_16x16x32_bf16 v[62:65], v[156:159], v[188:191], v[62:65]
	v_mfma_f32_16x16x32_bf16 v[58:61], v[164:167], v[188:191], v[58:61]
	v_mfma_f32_16x16x32_bf16 v[46:49], v[156:159], v[196:199], v[46:49]
	v_mfma_f32_16x16x32_bf16 v[42:45], v[164:167], v[196:199], v[42:45]
	v_mfma_f32_16x16x32_bf16 v[30:33], v[156:159], v[218:221], v[30:33]
	v_mfma_f32_16x16x32_bf16 v[26:29], v[164:167], v[218:221], v[26:29]
	v_mfma_f32_16x16x32_bf16 v[14:17], v[156:159], v[226:229], v[14:17]
	v_mfma_f32_16x16x32_bf16 v[10:13], v[164:167], v[226:229], v[10:13]
	s_setprio 0
	s_setprio 1
	v_mfma_f32_16x16x32_bf16 v[54:57], v[168:171], v[184:187], v[54:57]
	v_mfma_f32_16x16x32_bf16 v[50:53], v[176:179], v[184:187], v[50:53]
	v_mfma_f32_16x16x32_bf16 v[38:41], v[168:171], v[192:195], v[38:41]
	v_mfma_f32_16x16x32_bf16 v[34:37], v[176:179], v[192:195], v[34:37]
	v_mfma_f32_16x16x32_bf16 v[22:25], v[168:171], v[214:217], v[22:25]
	v_mfma_f32_16x16x32_bf16 v[18:21], v[176:179], v[214:217], v[18:21]
	v_mfma_f32_16x16x32_bf16 v[6:9], v[168:171], v[222:225], v[6:9]
	v_mfma_f32_16x16x32_bf16 v[2:5], v[176:179], v[222:225], v[2:5]
	v_mfma_f32_16x16x32_bf16 v[54:57], v[172:175], v[188:191], v[54:57]
	v_mfma_f32_16x16x32_bf16 v[50:53], v[180:183], v[188:191], v[50:53]
	v_mfma_f32_16x16x32_bf16 v[38:41], v[172:175], v[196:199], v[38:41]
	v_mfma_f32_16x16x32_bf16 v[34:37], v[180:183], v[196:199], v[34:37]
	v_mfma_f32_16x16x32_bf16 v[22:25], v[172:175], v[218:221], v[22:25]
	v_mfma_f32_16x16x32_bf16 v[18:21], v[180:183], v[218:221], v[18:21]
	v_mfma_f32_16x16x32_bf16 v[6:9], v[172:175], v[226:229], v[6:9]
	v_mfma_f32_16x16x32_bf16 v[2:5], v[180:183], v[226:229], v[2:5]
	s_setprio 0
	s_barrier
	s_add_u32 s40, s40, 0x100
	s_addc_u32 s41, s41, 0
	s_add_u32 s66, s66, 0x100
	s_addc_u32 s67, s67, 0
	s_cmp_ge_i32 s68, s62
	s_mov_b32 s42, s68
	s_cbranch_scc0 .LBB0_647
	s_and_b64 vcc, exec, s[44:45]
	s_cbranch_vccz .LBB0_650
	s_barrier

.LBB0_893:
	s_add_u32 s50, s48, 0xfffe0080
	s_addc_u32 s51, s49, -1
	s_add_i32 s57, 0, 0x10000
	s_cmp_eq_u32 s56, 4
	s_cselect_b32 s53, s19, s51
	s_cselect_b32 s52, s33, s50
	v_add_u32_e32 v98, s57, v144
	s_cselect_b32 s51, s37, s55
	s_cselect_b32 s50, s39, s54
	s_add_i32 s60, 0, 0x14000
	ds_read_b128 v[146:149], v98
	ds_read_b128 v[150:153], v98 offset:1024
	ds_read_b128 v[154:157], v98 offset:2048
	ds_read_b128 v[158:161], v98 offset:3072
	v_add_u32_e32 v98, s60, v144
	ds_read_b128 v[162:165], v98
	ds_read_b128 v[166:169], v98 offset:1024
	ds_read_b128 v[170:173], v98 offset:2048
	ds_read_b128 v[174:177], v98 offset:3072
	v_lshl_add_u64 v[198:199], s[48:49], 0, v[140:141]
	s_add_i32 m0, s4, 0xc000
	ds_read_b128 v[178:181], v145
	ds_read_b128 v[182:185], v145 offset:1024
	ds_read_b128 v[186:189], v145 offset:2048
	ds_read_b128 v[190:193], v145 offset:3072
	ds_read_b128 v[194:197], v145 offset:4096
	ds_read_b128 v[204:207], v145 offset:5120
	ds_read_b128 v[208:211], v145 offset:6144
	ds_read_b128 v[214:217], v145 offset:7168
	s_setprio 1
	global_load_lds_dwordx4 v[198:199], off
	v_lshl_add_u64 v[198:199], s[48:49], 0, v[142:143]
	s_add_i32 m0, s4, 0xe000
	s_nop 0
	global_load_lds_dwordx4 v[198:199], off
	s_waitcnt vmcnt(8)
	s_waitcnt lgkmcnt(0)
	s_barrier
	v_mfma_f32_16x16x32_bf16 v[128:131], v[146:149], v[178:181], v[128:131]
	v_mfma_f32_16x16x32_bf16 v[124:127], v[154:157], v[178:181], v[124:127]
	v_mfma_f32_16x16x32_bf16 v[112:115], v[146:149], v[186:189], v[112:115]
	v_mfma_f32_16x16x32_bf16 v[108:111], v[154:157], v[186:189], v[108:111]
	v_mfma_f32_16x16x32_bf16 v[94:97], v[146:149], v[194:197], v[94:97]
	v_mfma_f32_16x16x32_bf16 v[90:93], v[154:157], v[194:197], v[90:93]
	v_mfma_f32_16x16x32_bf16 v[78:81], v[146:149], v[208:211], v[78:81]
	v_mfma_f32_16x16x32_bf16 v[74:77], v[154:157], v[208:211], v[74:77]
	v_mfma_f32_16x16x32_bf16 v[128:131], v[150:153], v[182:185], v[128:131]
	v_mfma_f32_16x16x32_bf16 v[124:127], v[158:161], v[182:185], v[124:127]
	v_mfma_f32_16x16x32_bf16 v[112:115], v[150:153], v[190:193], v[112:115]
	v_mfma_f32_16x16x32_bf16 v[108:111], v[158:161], v[190:193], v[108:111]
	v_mfma_f32_16x16x32_bf16 v[94:97], v[150:153], v[204:207], v[94:97]
	v_mfma_f32_16x16x32_bf16 v[90:93], v[158:161], v[204:207], v[90:93]
	v_mfma_f32_16x16x32_bf16 v[78:81], v[150:153], v[214:217], v[78:81]
	v_mfma_f32_16x16x32_bf16 v[74:77], v[158:161], v[214:217], v[74:77]
	s_setprio 0
	s_setprio 1
	v_mfma_f32_16x16x32_bf16 v[120:123], v[162:165], v[178:181], v[120:123]
	v_mfma_f32_16x16x32_bf16 v[116:119], v[170:173], v[178:181], v[116:119]
	v_mfma_f32_16x16x32_bf16 v[104:107], v[162:165], v[186:189], v[104:107]
	v_mfma_f32_16x16x32_bf16 v[100:103], v[170:173], v[186:189], v[100:103]
	v_mfma_f32_16x16x32_bf16 v[86:89], v[162:165], v[194:197], v[86:89]
	v_mfma_f32_16x16x32_bf16 v[82:85], v[170:173], v[194:197], v[82:85]
	v_mfma_f32_16x16x32_bf16 v[70:73], v[162:165], v[208:211], v[70:73]
	v_mfma_f32_16x16x32_bf16 v[66:69], v[170:173], v[208:211], v[66:69]
	v_mfma_f32_16x16x32_bf16 v[120:123], v[166:169], v[182:185], v[120:123]
	v_mfma_f32_16x16x32_bf16 v[116:119], v[174:177], v[182:185], v[116:119]
	v_mfma_f32_16x16x32_bf16 v[104:107], v[166:169], v[190:193], v[104:107]
	v_mfma_f32_16x16x32_bf16 v[100:103], v[174:177], v[190:193], v[100:103]
	v_mfma_f32_16x16x32_bf16 v[86:89], v[166:169], v[204:207], v[86:89]
	v_mfma_f32_16x16x32_bf16 v[82:85], v[174:177], v[204:207], v[82:85]
	v_mfma_f32_16x16x32_bf16 v[70:73], v[166:169], v[214:217], v[70:73]
	v_mfma_f32_16x16x32_bf16 v[66:69], v[174:177], v[214:217], v[66:69]
	s_barrier
	s_add_i32 s57, s57, s2
	v_lshl_add_u64 v[198:199], s[50:51], 0, v[136:137]
	s_mov_b32 m0, s57
	ds_read_b128 v[178:181], v145 offset:16384
	ds_read_b128 v[182:185], v145 offset:17408
	ds_read_b128 v[186:189], v145 offset:18432
	ds_read_b128 v[190:193], v145 offset:19456
	ds_read_b128 v[194:197], v145 offset:20480
	ds_read_b128 v[204:207], v145 offset:21504
	ds_read_b128 v[208:211], v145 offset:22528
	ds_read_b128 v[214:217], v145 offset:23552
	global_load_lds_dwordx4 v[198:199], off
	s_add_i32 m0, s57, 0x2000
	s_add_u32 s58, s50, 0x20000
	v_lshl_add_u64 v[218:219], s[50:51], 0, v[132:133]
	s_addc_u32 s59, s51, 0
	s_add_i32 s57, s60, s2
	global_load_lds_dwordx4 v[218:219], off
	v_lshl_add_u64 v[220:221], s[58:59], 0, v[136:137]
	s_mov_b32 m0, s57
	v_lshl_add_u64 v[222:223], s[52:53], 0, v[134:135]
	global_load_lds_dwordx4 v[220:221], off
	v_lshl_add_u64 v[220:221], s[58:59], 0, v[132:133]
	s_add_i32 m0, s57, 0x2000
	s_nop 0
	global_load_lds_dwordx4 v[220:221], off
	v_lshl_add_u64 v[220:221], s[52:53], 0, v[138:139]
	s_mov_b32 m0, s4
	s_nop 0
	global_load_lds_dwordx4 v[220:221], off
	s_mov_b32 m0, s7
	s_nop 0
	global_load_lds_dwordx4 v[222:223], off
	s_waitcnt vmcnt(8)
	s_waitcnt lgkmcnt(0)
	s_barrier
	v_mfma_f32_16x16x32_bf16 v[62:65], v[146:149], v[178:181], v[62:65]
	v_mfma_f32_16x16x32_bf16 v[58:61], v[154:157], v[178:181], v[58:61]
	v_mfma_f32_16x16x32_bf16 v[46:49], v[146:149], v[186:189], v[46:49]
	v_mfma_f32_16x16x32_bf16 v[42:45], v[154:157], v[186:189], v[42:45]
	v_mfma_f32_16x16x32_bf16 v[30:33], v[146:149], v[194:197], v[30:33]
	v_mfma_f32_16x16x32_bf16 v[26:29], v[154:157], v[194:197], v[26:29]
	v_mfma_f32_16x16x32_bf16 v[14:17], v[146:149], v[208:211], v[14:17]
	v_mfma_f32_16x16x32_bf16 v[10:13], v[154:157], v[208:211], v[10:13]
	v_mfma_f32_16x16x32_bf16 v[62:65], v[150:153], v[182:185], v[62:65]
	v_mfma_f32_16x16x32_bf16 v[58:61], v[158:161], v[182:185], v[58:61]
	v_mfma_f32_16x16x32_bf16 v[46:49], v[150:153], v[190:193], v[46:49]
	v_mfma_f32_16x16x32_bf16 v[42:45], v[158:161], v[190:193], v[42:45]
	v_mfma_f32_16x16x32_bf16 v[30:33], v[150:153], v[204:207], v[30:33]
	v_mfma_f32_16x16x32_bf16 v[26:29], v[158:161], v[204:207], v[26:29]
	v_mfma_f32_16x16x32_bf16 v[14:17], v[150:153], v[214:217], v[14:17]
	v_mfma_f32_16x16x32_bf16 v[10:13], v[158:161], v[214:217], v[10:13]
	s_setprio 0
	s_setprio 1
	v_mfma_f32_16x16x32_bf16 v[54:57], v[162:165], v[178:181], v[54:57]
	v_mfma_f32_16x16x32_bf16 v[50:53], v[170:173], v[178:181], v[50:53]
	v_mfma_f32_16x16x32_bf16 v[38:41], v[162:165], v[186:189], v[38:41]
	v_mfma_f32_16x16x32_bf16 v[34:37], v[170:173], v[186:189], v[34:37]
	v_mfma_f32_16x16x32_bf16 v[22:25], v[162:165], v[194:197], v[22:25]
	v_mfma_f32_16x16x32_bf16 v[18:21], v[170:173], v[194:197], v[18:21]
	v_mfma_f32_16x16x32_bf16 v[6:9], v[162:165], v[208:211], v[6:9]
	v_mfma_f32_16x16x32_bf16 v[2:5], v[170:173], v[208:211], v[2:5]
	v_mfma_f32_16x16x32_bf16 v[54:57], v[166:169], v[182:185], v[54:57]
	v_mfma_f32_16x16x32_bf16 v[50:53], v[174:177], v[182:185], v[50:53]
	v_mfma_f32_16x16x32_bf16 v[38:41], v[166:169], v[190:193], v[38:41]
	v_mfma_f32_16x16x32_bf16 v[34:37], v[174:177], v[190:193], v[34:37]
	v_mfma_f32_16x16x32_bf16 v[22:25], v[166:169], v[204:207], v[22:25]
	v_mfma_f32_16x16x32_bf16 v[18:21], v[174:177], v[204:207], v[18:21]
	v_mfma_f32_16x16x32_bf16 v[6:9], v[166:169], v[214:217], v[6:9]
	v_mfma_f32_16x16x32_bf16 v[2:5], v[174:177], v[214:217], v[2:5]
	s_setprio 0
	s_barrier
	s_add_i32 s57, 0, 0x18000
	v_add_u32_e32 v98, s57, v144
	s_add_i32 s58, 0, 0x1c000
	ds_read_b128 v[146:149], v98
	ds_read_b128 v[150:153], v98 offset:1024
	ds_read_b128 v[154:157], v98 offset:2048
	ds_read_b128 v[158:161], v98 offset:3072
	v_add_u32_e32 v98, s58, v144
	ds_read_b128 v[162:165], v98
	ds_read_b128 v[166:169], v98 offset:1024
	ds_read_b128 v[170:173], v98 offset:2048
	ds_read_b128 v[174:177], v98 offset:3072
	s_add_u32 s52, s52, 0x20000
	s_addc_u32 s53, s53, 0
	s_mov_b32 m0, s8
	v_lshl_add_u64 v[224:225], s[52:53], 0, v[138:139]
	ds_read_b128 v[178:181], v145 offset:32768
	ds_read_b128 v[182:185], v145 offset:33792
	ds_read_b128 v[186:189], v145 offset:34816
	ds_read_b128 v[190:193], v145 offset:35840
	ds_read_b128 v[194:197], v145 offset:36864
	ds_read_b128 v[204:207], v145 offset:37888
	ds_read_b128 v[208:211], v145 offset:38912
	ds_read_b128 v[214:217], v145 offset:39936
	s_setprio 1
	global_load_lds_dwordx4 v[224:225], off
	v_lshl_add_u64 v[224:225], s[52:53], 0, v[134:135]
	s_mov_b32 m0, s9
	s_nop 0
	global_load_lds_dwordx4 v[224:225], off
	s_waitcnt vmcnt(8)
	s_waitcnt lgkmcnt(0)
	s_barrier
	v_mfma_f32_16x16x32_bf16 v[128:131], v[146:149], v[178:181], v[128:131]
	v_mfma_f32_16x16x32_bf16 v[124:127], v[154:157], v[178:181], v[124:127]
	v_mfma_f32_16x16x32_bf16 v[112:115], v[146:149], v[186:189], v[112:115]
	v_mfma_f32_16x16x32_bf16 v[108:111], v[154:157], v[186:189], v[108:111]
	v_mfma_f32_16x16x32_bf16 v[94:97], v[146:149], v[194:197], v[94:97]
	v_mfma_f32_16x16x32_bf16 v[90:93], v[154:157], v[194:197], v[90:93]
	v_mfma_f32_16x16x32_bf16 v[78:81], v[146:149], v[208:211], v[78:81]
	v_mfma_f32_16x16x32_bf16 v[74:77], v[154:157], v[208:211], v[74:77]
	v_mfma_f32_16x16x32_bf16 v[128:131], v[150:153], v[182:185], v[128:131]
	v_mfma_f32_16x16x32_bf16 v[124:127], v[158:161], v[182:185], v[124:127]
	v_mfma_f32_16x16x32_bf16 v[112:115], v[150:153], v[190:193], v[112:115]
	v_mfma_f32_16x16x32_bf16 v[108:111], v[158:161], v[190:193], v[108:111]
	v_mfma_f32_16x16x32_bf16 v[94:97], v[150:153], v[204:207], v[94:97]
	v_mfma_f32_16x16x32_bf16 v[90:93], v[158:161], v[204:207], v[90:93]
	v_mfma_f32_16x16x32_bf16 v[78:81], v[150:153], v[214:217], v[78:81]
	v_mfma_f32_16x16x32_bf16 v[74:77], v[158:161], v[214:217], v[74:77]
	s_setprio 0
	s_setprio 1
	v_mfma_f32_16x16x32_bf16 v[120:123], v[162:165], v[178:181], v[120:123]
	v_mfma_f32_16x16x32_bf16 v[116:119], v[170:173], v[178:181], v[116:119]
	v_mfma_f32_16x16x32_bf16 v[104:107], v[162:165], v[186:189], v[104:107]
	v_mfma_f32_16x16x32_bf16 v[100:103], v[170:173], v[186:189], v[100:103]
	v_mfma_f32_16x16x32_bf16 v[86:89], v[162:165], v[194:197], v[86:89]
	v_mfma_f32_16x16x32_bf16 v[82:85], v[170:173], v[194:197], v[82:85]
	v_mfma_f32_16x16x32_bf16 v[70:73], v[162:165], v[208:211], v[70:73]
	v_mfma_f32_16x16x32_bf16 v[66:69], v[170:173], v[208:211], v[66:69]
	v_mfma_f32_16x16x32_bf16 v[120:123], v[166:169], v[182:185], v[120:123]
	v_mfma_f32_16x16x32_bf16 v[116:119], v[174:177], v[182:185], v[116:119]
	v_mfma_f32_16x16x32_bf16 v[104:107], v[166:169], v[190:193], v[104:107]
	v_mfma_f32_16x16x32_bf16 v[100:103], v[174:177], v[190:193], v[100:103]
	v_mfma_f32_16x16x32_bf16 v[86:89], v[166:169], v[204:207], v[86:89]
	v_mfma_f32_16x16x32_bf16 v[82:85], v[174:177], v[204:207], v[82:85]
	v_mfma_f32_16x16x32_bf16 v[70:73], v[166:169], v[214:217], v[70:73]
	v_mfma_f32_16x16x32_bf16 v[66:69], v[174:177], v[214:217], v[66:69]
	s_barrier
	s_add_i32 s52, s57, s2
	v_lshl_add_u64 v[198:199], v[198:199], 0, s[28:29]
	s_mov_b32 m0, s52
	ds_read_b128 v[178:181], v145 offset:49152
	ds_read_b128 v[182:185], v145 offset:50176
	ds_read_b128 v[186:189], v145 offset:51200
	ds_read_b128 v[190:193], v145 offset:52224
	ds_read_b128 v[194:197], v145 offset:53248
	ds_read_b128 v[204:207], v145 offset:54272
	ds_read_b128 v[208:211], v145 offset:55296
	ds_read_b128 v[214:217], v145 offset:56320
	global_load_lds_dwordx4 v[198:199], off
	s_add_i32 m0, s52, 0x2000
	s_add_u32 s50, s50, 0x20080
	v_lshl_add_u64 v[198:199], v[218:219], 0, s[28:29]
	s_addc_u32 s51, s51, 0
	s_add_i32 s52, s58, s2
	global_load_lds_dwordx4 v[198:199], off
	v_lshl_add_u64 v[198:199], s[50:51], 0, v[136:137]
	s_mov_b32 m0, s52
	s_nop 0
	global_load_lds_dwordx4 v[198:199], off
	v_lshl_add_u64 v[198:199], s[50:51], 0, v[132:133]
	s_add_i32 m0, s52, 0x2000
	s_nop 0
	global_load_lds_dwordx4 v[198:199], off
	v_lshl_add_u64 v[198:199], v[220:221], 0, s[28:29]
	s_mov_b32 m0, s12
	s_nop 0
	global_load_lds_dwordx4 v[198:199], off
	v_lshl_add_u64 v[198:199], v[222:223], 0, s[28:29]
	s_mov_b32 m0, s13
	s_nop 0
	global_load_lds_dwordx4 v[198:199], off
	s_waitcnt vmcnt(8)
	s_waitcnt lgkmcnt(0)
	s_barrier
	v_mfma_f32_16x16x32_bf16 v[62:65], v[146:149], v[178:181], v[62:65]
	v_mfma_f32_16x16x32_bf16 v[58:61], v[154:157], v[178:181], v[58:61]
	v_mfma_f32_16x16x32_bf16 v[46:49], v[146:149], v[186:189], v[46:49]
	v_mfma_f32_16x16x32_bf16 v[42:45], v[154:157], v[186:189], v[42:45]
	v_mfma_f32_16x16x32_bf16 v[30:33], v[146:149], v[194:197], v[30:33]
	v_mfma_f32_16x16x32_bf16 v[26:29], v[154:157], v[194:197], v[26:29]
	v_mfma_f32_16x16x32_bf16 v[14:17], v[146:149], v[208:211], v[14:17]
	v_mfma_f32_16x16x32_bf16 v[10:13], v[154:157], v[208:211], v[10:13]
	v_mfma_f32_16x16x32_bf16 v[62:65], v[150:153], v[182:185], v[62:65]
	v_mfma_f32_16x16x32_bf16 v[58:61], v[158:161], v[182:185], v[58:61]
	v_mfma_f32_16x16x32_bf16 v[46:49], v[150:153], v[190:193], v[46:49]
	v_mfma_f32_16x16x32_bf16 v[42:45], v[158:161], v[190:193], v[42:45]
	v_mfma_f32_16x16x32_bf16 v[30:33], v[150:153], v[204:207], v[30:33]
	v_mfma_f32_16x16x32_bf16 v[26:29], v[158:161], v[204:207], v[26:29]
	v_mfma_f32_16x16x32_bf16 v[14:17], v[150:153], v[214:217], v[14:17]
	v_mfma_f32_16x16x32_bf16 v[10:13], v[158:161], v[214:217], v[10:13]
	s_setprio 0
	s_setprio 1
	v_mfma_f32_16x16x32_bf16 v[54:57], v[162:165], v[178:181], v[54:57]
	v_mfma_f32_16x16x32_bf16 v[50:53], v[170:173], v[178:181], v[50:53]
	v_mfma_f32_16x16x32_bf16 v[38:41], v[162:165], v[186:189], v[38:41]
	v_mfma_f32_16x16x32_bf16 v[34:37], v[170:173], v[186:189], v[34:37]
	v_mfma_f32_16x16x32_bf16 v[22:25], v[162:165], v[194:197], v[22:25]
	v_mfma_f32_16x16x32_bf16 v[18:21], v[170:173], v[194:197], v[18:21]
	v_mfma_f32_16x16x32_bf16 v[6:9], v[162:165], v[208:211], v[6:9]
	v_mfma_f32_16x16x32_bf16 v[2:5], v[170:173], v[208:211], v[2:5]
	v_mfma_f32_16x16x32_bf16 v[54:57], v[166:169], v[182:185], v[54:57]
	v_mfma_f32_16x16x32_bf16 v[50:53], v[174:177], v[182:185], v[50:53]
	v_mfma_f32_16x16x32_bf16 v[38:41], v[166:169], v[190:193], v[38:41]
	v_mfma_f32_16x16x32_bf16 v[34:37], v[174:177], v[190:193], v[34:37]
	v_mfma_f32_16x16x32_bf16 v[22:25], v[166:169], v[204:207], v[22:25]
	v_mfma_f32_16x16x32_bf16 v[18:21], v[174:177], v[204:207], v[18:21]
	v_mfma_f32_16x16x32_bf16 v[6:9], v[166:169], v[214:217], v[6:9]
	v_mfma_f32_16x16x32_bf16 v[2:5], v[174:177], v[214:217], v[2:5]
	s_setprio 0
	s_barrier
	s_add_i32 s56, s56, 2
	s_add_u32 s48, s48, 0x100
	s_addc_u32 s49, s49, 0
	s_add_u32 s54, s54, 0x100
	s_addc_u32 s55, s55, 0
	s_cmp_gt_u32 s56, 5
	s_cbranch_scc0 .LBB0_893
	s_and_b64 vcc, exec, s[22:23]
	s_cbranch_vccz .LBB0_896
	s_barrier

.LBB0_1072:
	s_add_u32 s60, s56, s58
	s_addc_u32 s61, s57, s59
	s_add_u32 s60, s60, 0x100
	s_addc_u32 s61, s61, 0
	s_add_u32 s71, s66, s58
	s_addc_u32 s72, s67, s59
	s_add_i32 s73, 0, 0x10000
	s_cmpk_eq_i32 s58, 0x700
	s_cselect_b32 s63, s45, s61
	s_cselect_b32 s62, s51, s60
	v_add_u32_e32 v98, s73, v214
	s_cselect_b32 s61, s49, s72
	s_cselect_b32 s60, s65, s71
	s_add_i32 s71, 0, 0x14000
	ds_read_b128 v[138:141], v98
	ds_read_b128 v[142:145], v98 offset:1024
	ds_read_b128 v[146:149], v98 offset:2048
	ds_read_b128 v[150:153], v98 offset:3072
	v_add_u32_e32 v98, s71, v214
	ds_read_b128 v[154:157], v98
	ds_read_b128 v[158:161], v98 offset:1024
	ds_read_b128 v[162:165], v98 offset:2048
	ds_read_b128 v[166:169], v98 offset:3072
	v_lshl_add_u64 v[100:101], v[134:135], 0, s[58:59]
	s_add_i32 m0, s9, 0xc000
	ds_read_b128 v[170:173], v218
	ds_read_b128 v[186:189], v218 offset:1024
	ds_read_b128 v[190:193], v218 offset:2048
	ds_read_b128 v[194:197], v218 offset:3072
	ds_read_b128 v[204:207], v218 offset:4096
	ds_read_b128 v[208:211], v218 offset:5120
	ds_read_b128 v[220:223], v218 offset:6144
	ds_read_b128 v[224:227], v218 offset:7168
	s_setprio 1
	global_load_lds_dwordx4 v[100:101], off
	v_lshl_add_u64 v[100:101], v[136:137], 0, s[58:59]
	s_add_i32 m0, s9, 0xe000
	s_nop 0
	global_load_lds_dwordx4 v[100:101], off
	s_waitcnt vmcnt(8)
	s_waitcnt lgkmcnt(0)
	s_barrier
	v_mfma_f32_16x16x32_bf16 v[130:133], v[138:141], v[170:173], v[130:133]
	v_mfma_f32_16x16x32_bf16 v[126:129], v[146:149], v[170:173], v[126:129]
	v_mfma_f32_16x16x32_bf16 v[122:125], v[138:141], v[190:193], v[122:125]
	v_mfma_f32_16x16x32_bf16 v[118:121], v[146:149], v[190:193], v[118:121]
	v_mfma_f32_16x16x32_bf16 v[114:117], v[138:141], v[204:207], v[114:117]
	v_mfma_f32_16x16x32_bf16 v[110:113], v[146:149], v[204:207], v[110:113]
	v_mfma_f32_16x16x32_bf16 v[106:109], v[138:141], v[220:223], v[106:109]
	v_mfma_f32_16x16x32_bf16 v[100:103], v[146:149], v[220:223], v[102:105]
	v_mfma_f32_16x16x32_bf16 v[130:133], v[142:145], v[186:189], v[130:133]
	v_mfma_f32_16x16x32_bf16 v[126:129], v[150:153], v[186:189], v[126:129]
	v_mfma_f32_16x16x32_bf16 v[122:125], v[142:145], v[194:197], v[122:125]
	v_mfma_f32_16x16x32_bf16 v[118:121], v[150:153], v[194:197], v[118:121]
	v_mfma_f32_16x16x32_bf16 v[114:117], v[142:145], v[208:211], v[114:117]
	v_mfma_f32_16x16x32_bf16 v[110:113], v[150:153], v[208:211], v[110:113]
	v_mfma_f32_16x16x32_bf16 v[106:109], v[142:145], v[224:227], v[106:109]
	v_mfma_f32_16x16x32_bf16 v[100:103], v[150:153], v[224:227], v[100:103]
	s_setprio 0
	s_setprio 1
	v_mfma_f32_16x16x32_bf16 v[62:65], v[154:157], v[170:173], v[62:65]
	v_mfma_f32_16x16x32_bf16 v[58:61], v[162:165], v[170:173], v[58:61]
	v_mfma_f32_16x16x32_bf16 v[54:57], v[154:157], v[190:193], v[54:57]
	v_mfma_f32_16x16x32_bf16 v[50:53], v[162:165], v[190:193], v[50:53]
	v_mfma_f32_16x16x32_bf16 v[46:49], v[154:157], v[204:207], v[46:49]
	v_mfma_f32_16x16x32_bf16 v[42:45], v[162:165], v[204:207], v[42:45]
	v_mfma_f32_16x16x32_bf16 v[38:41], v[154:157], v[220:223], v[38:41]
	v_mfma_f32_16x16x32_bf16 v[34:37], v[162:165], v[220:223], v[34:37]
	v_mfma_f32_16x16x32_bf16 v[62:65], v[158:161], v[186:189], v[62:65]
	v_mfma_f32_16x16x32_bf16 v[58:61], v[166:169], v[186:189], v[58:61]
	v_mfma_f32_16x16x32_bf16 v[54:57], v[158:161], v[194:197], v[54:57]
	v_mfma_f32_16x16x32_bf16 v[50:53], v[166:169], v[194:197], v[50:53]
	v_mfma_f32_16x16x32_bf16 v[46:49], v[158:161], v[208:211], v[46:49]
	v_mfma_f32_16x16x32_bf16 v[42:45], v[166:169], v[208:211], v[42:45]
	v_mfma_f32_16x16x32_bf16 v[38:41], v[158:161], v[224:227], v[38:41]
	v_mfma_f32_16x16x32_bf16 v[34:37], v[166:169], v[224:227], v[34:37]
	s_barrier
	s_add_i32 s72, s73, s4
	v_lshl_add_u64 v[198:199], s[60:61], 0, v[176:177]
	s_mov_b32 m0, s72
	ds_read_b128 v[170:173], v218 offset:16384
	ds_read_b128 v[186:189], v218 offset:17408
	ds_read_b128 v[190:193], v218 offset:18432
	ds_read_b128 v[194:197], v218 offset:19456
	ds_read_b128 v[204:207], v218 offset:20480
	ds_read_b128 v[208:211], v218 offset:21504
	ds_read_b128 v[220:223], v218 offset:22528
	ds_read_b128 v[224:227], v218 offset:23552
	global_load_lds_dwordx4 v[198:199], off
	s_add_i32 m0, s72, 0x2000
	s_add_u32 s72, s60, 0x40000
	v_lshl_add_u64 v[228:229], s[60:61], 0, v[180:181]
	s_addc_u32 s73, s61, 0
	s_add_i32 s71, s71, s4
	global_load_lds_dwordx4 v[228:229], off
	v_lshl_add_u64 v[104:105], s[72:73], 0, v[176:177]
	s_mov_b32 m0, s71
	v_lshl_add_u64 v[230:231], s[62:63], 0, v[174:175]
	global_load_lds_dwordx4 v[104:105], off
	v_lshl_add_u64 v[104:105], s[72:73], 0, v[180:181]
	s_add_i32 m0, s71, 0x2000
	v_lshl_add_u64 v[232:233], s[62:63], 0, v[178:179]
	global_load_lds_dwordx4 v[104:105], off
	s_mov_b32 m0, s9
	s_nop 0
	global_load_lds_dwordx4 v[230:231], off
	s_mov_b32 m0, s10
	s_nop 0
	global_load_lds_dwordx4 v[232:233], off
	s_waitcnt vmcnt(8)
	s_waitcnt lgkmcnt(0)
	s_barrier
	v_mfma_f32_16x16x32_bf16 v[94:97], v[138:141], v[170:173], v[94:97]
	v_mfma_f32_16x16x32_bf16 v[90:93], v[146:149], v[170:173], v[90:93]
	v_mfma_f32_16x16x32_bf16 v[86:89], v[138:141], v[190:193], v[86:89]
	v_mfma_f32_16x16x32_bf16 v[82:85], v[146:149], v[190:193], v[82:85]
	v_mfma_f32_16x16x32_bf16 v[78:81], v[138:141], v[204:207], v[78:81]
	v_mfma_f32_16x16x32_bf16 v[74:77], v[146:149], v[204:207], v[74:77]
	v_mfma_f32_16x16x32_bf16 v[70:73], v[138:141], v[220:223], v[70:73]
	v_mfma_f32_16x16x32_bf16 v[66:69], v[146:149], v[220:223], v[66:69]
	v_mfma_f32_16x16x32_bf16 v[94:97], v[142:145], v[186:189], v[94:97]
	v_mfma_f32_16x16x32_bf16 v[90:93], v[150:153], v[186:189], v[90:93]
	v_mfma_f32_16x16x32_bf16 v[86:89], v[142:145], v[194:197], v[86:89]
	v_mfma_f32_16x16x32_bf16 v[82:85], v[150:153], v[194:197], v[82:85]
	v_mfma_f32_16x16x32_bf16 v[78:81], v[142:145], v[208:211], v[78:81]
	v_mfma_f32_16x16x32_bf16 v[74:77], v[150:153], v[208:211], v[74:77]
	v_mfma_f32_16x16x32_bf16 v[70:73], v[142:145], v[224:227], v[70:73]
	v_mfma_f32_16x16x32_bf16 v[66:69], v[150:153], v[224:227], v[66:69]
	s_setprio 0
	s_setprio 1
	v_mfma_f32_16x16x32_bf16 v[30:33], v[154:157], v[170:173], v[30:33]
	v_mfma_f32_16x16x32_bf16 v[26:29], v[162:165], v[170:173], v[26:29]
	v_mfma_f32_16x16x32_bf16 v[22:25], v[154:157], v[190:193], v[22:25]
	v_mfma_f32_16x16x32_bf16 v[18:21], v[162:165], v[190:193], v[18:21]
	v_mfma_f32_16x16x32_bf16 v[14:17], v[154:157], v[204:207], v[14:17]
	v_mfma_f32_16x16x32_bf16 v[10:13], v[162:165], v[204:207], v[10:13]
	v_mfma_f32_16x16x32_bf16 v[6:9], v[154:157], v[220:223], v[6:9]
	v_mfma_f32_16x16x32_bf16 v[2:5], v[162:165], v[220:223], v[2:5]
	v_mfma_f32_16x16x32_bf16 v[30:33], v[158:161], v[186:189], v[30:33]
	v_mfma_f32_16x16x32_bf16 v[26:29], v[166:169], v[186:189], v[26:29]
	v_mfma_f32_16x16x32_bf16 v[22:25], v[158:161], v[194:197], v[22:25]
	v_mfma_f32_16x16x32_bf16 v[18:21], v[166:169], v[194:197], v[18:21]
	v_mfma_f32_16x16x32_bf16 v[14:17], v[158:161], v[208:211], v[14:17]
	v_mfma_f32_16x16x32_bf16 v[10:13], v[166:169], v[208:211], v[10:13]
	v_mfma_f32_16x16x32_bf16 v[6:9], v[158:161], v[224:227], v[6:9]
	v_mfma_f32_16x16x32_bf16 v[2:5], v[166:169], v[224:227], v[2:5]
	s_setprio 0
	s_barrier
	s_add_i32 s71, 0, 0x18000
	v_add_u32_e32 v98, s71, v214
	s_add_i32 s72, 0, 0x1c000
	ds_read_b128 v[138:141], v98
	ds_read_b128 v[142:145], v98 offset:1024
	ds_read_b128 v[146:149], v98 offset:2048
	ds_read_b128 v[150:153], v98 offset:3072
	v_add_u32_e32 v98, s72, v214
	ds_read_b128 v[154:157], v98
	ds_read_b128 v[158:161], v98 offset:1024
	ds_read_b128 v[162:165], v98 offset:2048
	ds_read_b128 v[166:169], v98 offset:3072
	s_add_u32 s62, s62, 0x40000
	s_addc_u32 s63, s63, 0
	s_mov_b32 m0, s11
	v_lshl_add_u64 v[104:105], s[62:63], 0, v[174:175]
	ds_read_b128 v[170:173], v218 offset:32768
	ds_read_b128 v[186:189], v218 offset:33792
	ds_read_b128 v[190:193], v218 offset:34816
	ds_read_b128 v[194:197], v218 offset:35840
	ds_read_b128 v[204:207], v218 offset:36864
	ds_read_b128 v[208:211], v218 offset:37888
	ds_read_b128 v[220:223], v218 offset:38912
	ds_read_b128 v[224:227], v218 offset:39936
	s_setprio 1
	global_load_lds_dwordx4 v[104:105], off
	v_lshl_add_u64 v[104:105], s[62:63], 0, v[178:179]
	s_mov_b32 m0, s12
	s_nop 0
	global_load_lds_dwordx4 v[104:105], off
	s_waitcnt vmcnt(8)
	s_waitcnt lgkmcnt(0)
	s_barrier
	v_mfma_f32_16x16x32_bf16 v[130:133], v[138:141], v[170:173], v[130:133]
	v_mfma_f32_16x16x32_bf16 v[126:129], v[146:149], v[170:173], v[126:129]
	v_mfma_f32_16x16x32_bf16 v[122:125], v[138:141], v[190:193], v[122:125]
	v_mfma_f32_16x16x32_bf16 v[118:121], v[146:149], v[190:193], v[118:121]
	v_mfma_f32_16x16x32_bf16 v[114:117], v[138:141], v[204:207], v[114:117]
	v_mfma_f32_16x16x32_bf16 v[110:113], v[146:149], v[204:207], v[110:113]
	v_mfma_f32_16x16x32_bf16 v[104:107], v[138:141], v[220:223], v[106:109]
	v_mfma_f32_16x16x32_bf16 v[100:103], v[146:149], v[220:223], v[100:103]
	v_mfma_f32_16x16x32_bf16 v[130:133], v[142:145], v[186:189], v[130:133]
	v_mfma_f32_16x16x32_bf16 v[126:129], v[150:153], v[186:189], v[126:129]
	v_mfma_f32_16x16x32_bf16 v[122:125], v[142:145], v[194:197], v[122:125]
	v_mfma_f32_16x16x32_bf16 v[118:121], v[150:153], v[194:197], v[118:121]
	v_mfma_f32_16x16x32_bf16 v[114:117], v[142:145], v[208:211], v[114:117]
	v_mfma_f32_16x16x32_bf16 v[110:113], v[150:153], v[208:211], v[110:113]
	v_mfma_f32_16x16x32_bf16 v[106:109], v[142:145], v[224:227], v[104:107]
	v_mfma_f32_16x16x32_bf16 v[102:105], v[150:153], v[224:227], v[100:103]
	s_setprio 0
	s_setprio 1
	v_mfma_f32_16x16x32_bf16 v[62:65], v[154:157], v[170:173], v[62:65]
	v_mfma_f32_16x16x32_bf16 v[58:61], v[162:165], v[170:173], v[58:61]
	v_mfma_f32_16x16x32_bf16 v[54:57], v[154:157], v[190:193], v[54:57]
	v_mfma_f32_16x16x32_bf16 v[50:53], v[162:165], v[190:193], v[50:53]
	v_mfma_f32_16x16x32_bf16 v[46:49], v[154:157], v[204:207], v[46:49]
	v_mfma_f32_16x16x32_bf16 v[42:45], v[162:165], v[204:207], v[42:45]
	v_mfma_f32_16x16x32_bf16 v[38:41], v[154:157], v[220:223], v[38:41]
	v_mfma_f32_16x16x32_bf16 v[34:37], v[162:165], v[220:223], v[34:37]
	v_mfma_f32_16x16x32_bf16 v[62:65], v[158:161], v[186:189], v[62:65]
	v_mfma_f32_16x16x32_bf16 v[58:61], v[166:169], v[186:189], v[58:61]
	v_mfma_f32_16x16x32_bf16 v[54:57], v[158:161], v[194:197], v[54:57]
	v_mfma_f32_16x16x32_bf16 v[50:53], v[166:169], v[194:197], v[50:53]
	v_mfma_f32_16x16x32_bf16 v[46:49], v[158:161], v[208:211], v[46:49]
	v_mfma_f32_16x16x32_bf16 v[42:45], v[166:169], v[208:211], v[42:45]
	v_mfma_f32_16x16x32_bf16 v[38:41], v[158:161], v[224:227], v[38:41]
	v_mfma_f32_16x16x32_bf16 v[34:37], v[166:169], v[224:227], v[34:37]
	s_barrier
	s_add_i32 s62, s71, s4
	v_lshl_add_u64 v[100:101], v[198:199], 0, s[28:29]
	s_mov_b32 m0, s62
	ds_read_b128 v[170:173], v218 offset:49152
	ds_read_b128 v[186:189], v218 offset:50176
	ds_read_b128 v[190:193], v218 offset:51200
	ds_read_b128 v[194:197], v218 offset:52224
	ds_read_b128 v[204:207], v218 offset:53248
	ds_read_b128 v[208:211], v218 offset:54272
	ds_read_b128 v[220:223], v218 offset:55296
	ds_read_b128 v[224:227], v218 offset:56320
	global_load_lds_dwordx4 v[100:101], off
	s_add_i32 m0, s62, 0x2000
	s_add_u32 s60, s60, 0x40080
	v_lshl_add_u64 v[100:101], v[228:229], 0, s[28:29]
	s_addc_u32 s61, s61, 0
	s_add_i32 s62, s72, s4
	global_load_lds_dwordx4 v[100:101], off
	v_lshl_add_u64 v[100:101], s[60:61], 0, v[176:177]
	s_mov_b32 m0, s62
	s_nop 0
	global_load_lds_dwordx4 v[100:101], off
	v_lshl_add_u64 v[100:101], s[60:61], 0, v[180:181]
	s_add_i32 m0, s62, 0x2000
	s_nop 0
	global_load_lds_dwordx4 v[100:101], off
	v_lshl_add_u64 v[100:101], v[230:231], 0, s[28:29]
	s_mov_b32 m0, s15
	s_nop 0
	global_load_lds_dwordx4 v[100:101], off
	v_lshl_add_u64 v[100:101], v[232:233], 0, s[28:29]
	s_mov_b32 m0, s16
	s_nop 0
	global_load_lds_dwordx4 v[100:101], off
	s_waitcnt vmcnt(8)
	s_waitcnt lgkmcnt(0)
	s_barrier
	v_mfma_f32_16x16x32_bf16 v[94:97], v[138:141], v[170:173], v[94:97]
	v_mfma_f32_16x16x32_bf16 v[90:93], v[146:149], v[170:173], v[90:93]
	v_mfma_f32_16x16x32_bf16 v[86:89], v[138:141], v[190:193], v[86:89]
	v_mfma_f32_16x16x32_bf16 v[82:85], v[146:149], v[190:193], v[82:85]
	v_mfma_f32_16x16x32_bf16 v[78:81], v[138:141], v[204:207], v[78:81]
	v_mfma_f32_16x16x32_bf16 v[74:77], v[146:149], v[204:207], v[74:77]
	v_mfma_f32_16x16x32_bf16 v[70:73], v[138:141], v[220:223], v[70:73]
	v_mfma_f32_16x16x32_bf16 v[66:69], v[146:149], v[220:223], v[66:69]
	v_mfma_f32_16x16x32_bf16 v[94:97], v[142:145], v[186:189], v[94:97]
	v_mfma_f32_16x16x32_bf16 v[90:93], v[150:153], v[186:189], v[90:93]
	v_mfma_f32_16x16x32_bf16 v[86:89], v[142:145], v[194:197], v[86:89]
	v_mfma_f32_16x16x32_bf16 v[82:85], v[150:153], v[194:197], v[82:85]
	v_mfma_f32_16x16x32_bf16 v[78:81], v[142:145], v[208:211], v[78:81]
	v_mfma_f32_16x16x32_bf16 v[74:77], v[150:153], v[208:211], v[74:77]
	v_mfma_f32_16x16x32_bf16 v[70:73], v[142:145], v[224:227], v[70:73]
	v_mfma_f32_16x16x32_bf16 v[66:69], v[150:153], v[224:227], v[66:69]
	s_setprio 0
	s_setprio 1
	v_mfma_f32_16x16x32_bf16 v[30:33], v[154:157], v[170:173], v[30:33]
	v_mfma_f32_16x16x32_bf16 v[26:29], v[162:165], v[170:173], v[26:29]
	v_mfma_f32_16x16x32_bf16 v[22:25], v[154:157], v[190:193], v[22:25]
	v_mfma_f32_16x16x32_bf16 v[18:21], v[162:165], v[190:193], v[18:21]
	v_mfma_f32_16x16x32_bf16 v[14:17], v[154:157], v[204:207], v[14:17]
	v_mfma_f32_16x16x32_bf16 v[10:13], v[162:165], v[204:207], v[10:13]
	v_mfma_f32_16x16x32_bf16 v[6:9], v[154:157], v[220:223], v[6:9]
	v_mfma_f32_16x16x32_bf16 v[2:5], v[162:165], v[220:223], v[2:5]
	v_mfma_f32_16x16x32_bf16 v[30:33], v[158:161], v[186:189], v[30:33]
	v_mfma_f32_16x16x32_bf16 v[26:29], v[166:169], v[186:189], v[26:29]
	v_mfma_f32_16x16x32_bf16 v[22:25], v[158:161], v[194:197], v[22:25]
	v_mfma_f32_16x16x32_bf16 v[18:21], v[166:169], v[194:197], v[18:21]
	v_mfma_f32_16x16x32_bf16 v[14:17], v[158:161], v[208:211], v[14:17]
	v_mfma_f32_16x16x32_bf16 v[10:13], v[166:169], v[208:211], v[10:13]
	v_mfma_f32_16x16x32_bf16 v[6:9], v[158:161], v[224:227], v[6:9]
	v_mfma_f32_16x16x32_bf16 v[2:5], v[166:169], v[224:227], v[2:5]
	s_setprio 0
	s_barrier
	s_add_u32 s58, s58, 0x100
	s_addc_u32 s59, s59, 0
	s_cmp_gt_u32 s70, 13
	s_cbranch_scc1 .LBB0_1075

.LBB0_1110:
	s_add_i32 s75, s75, 2
	s_add_u32 s60, s38, s58
	s_addc_u32 s61, s39, s59
	s_add_u32 s60, s60, 0x100
	s_addc_u32 s61, s61, 0
	s_add_u32 s76, s72, s58
	s_addc_u32 s77, s73, s59
	s_add_i32 s78, 0, 0x10000
	s_cmp_eq_u32 s74, s58
	s_cselect_b32 s63, s49, s61
	s_cselect_b32 s62, s70, s60
	v_add_u32_e32 v98, s78, v177
	s_cselect_b32 s61, s45, s77
	s_cselect_b32 s60, s71, s76
	s_add_i32 s79, 0, 0x14000
	ds_read_b128 v[138:141], v98
	ds_read_b128 v[142:145], v98 offset:1024
	ds_read_b128 v[146:149], v98 offset:2048
	ds_read_b128 v[150:153], v98 offset:3072
	v_add_u32_e32 v98, s79, v177
	ds_read_b128 v[154:157], v98
	ds_read_b128 v[170:173], v98 offset:1024
	ds_read_b128 v[182:185], v98 offset:2048
	ds_read_b128 v[186:189], v98 offset:3072
	v_lshl_add_u64 v[100:101], v[134:135], 0, s[58:59]
	s_add_i32 m0, s10, 0xc000
	ds_read_b128 v[190:193], v181
	ds_read_b128 v[194:197], v181 offset:1024
	ds_read_b128 v[204:207], v181 offset:2048
	ds_read_b128 v[208:211], v181 offset:3072
	ds_read_b128 v[214:217], v181 offset:4096
	ds_read_b128 v[218:221], v181 offset:5120
	ds_read_b128 v[222:225], v181 offset:6144
	ds_read_b128 v[226:229], v181 offset:7168
	s_setprio 1
	global_load_lds_dwordx4 v[100:101], off
	v_lshl_add_u64 v[100:101], v[136:137], 0, s[58:59]
	s_add_i32 m0, s10, 0xe000
	s_nop 0
	global_load_lds_dwordx4 v[100:101], off
	s_waitcnt vmcnt(8)
	s_waitcnt lgkmcnt(0)
	s_barrier
	v_mfma_f32_16x16x32_bf16 v[130:133], v[138:141], v[190:193], v[130:133]
	v_mfma_f32_16x16x32_bf16 v[126:129], v[146:149], v[190:193], v[126:129]
	v_mfma_f32_16x16x32_bf16 v[114:117], v[138:141], v[204:207], v[114:117]
	v_mfma_f32_16x16x32_bf16 v[110:113], v[146:149], v[204:207], v[110:113]
	v_mfma_f32_16x16x32_bf16 v[94:97], v[138:141], v[214:217], v[94:97]
	v_mfma_f32_16x16x32_bf16 v[90:93], v[146:149], v[214:217], v[90:93]
	v_mfma_f32_16x16x32_bf16 v[78:81], v[138:141], v[222:225], v[78:81]
	v_mfma_f32_16x16x32_bf16 v[74:77], v[146:149], v[222:225], v[74:77]
	v_mfma_f32_16x16x32_bf16 v[130:133], v[142:145], v[194:197], v[130:133]
	v_mfma_f32_16x16x32_bf16 v[126:129], v[150:153], v[194:197], v[126:129]
	v_mfma_f32_16x16x32_bf16 v[114:117], v[142:145], v[208:211], v[114:117]
	v_mfma_f32_16x16x32_bf16 v[110:113], v[150:153], v[208:211], v[110:113]
	v_mfma_f32_16x16x32_bf16 v[94:97], v[142:145], v[218:221], v[94:97]
	v_mfma_f32_16x16x32_bf16 v[90:93], v[150:153], v[218:221], v[90:93]
	v_mfma_f32_16x16x32_bf16 v[78:81], v[142:145], v[226:229], v[78:81]
	v_mfma_f32_16x16x32_bf16 v[74:77], v[150:153], v[226:229], v[74:77]
	s_setprio 0
	s_setprio 1
	v_mfma_f32_16x16x32_bf16 v[122:125], v[154:157], v[190:193], v[122:125]
	v_mfma_f32_16x16x32_bf16 v[118:121], v[182:185], v[190:193], v[118:121]
	v_mfma_f32_16x16x32_bf16 v[106:109], v[154:157], v[204:207], v[106:109]
	v_mfma_f32_16x16x32_bf16 v[100:103], v[182:185], v[204:207], v[102:105]
	v_mfma_f32_16x16x32_bf16 v[86:89], v[154:157], v[214:217], v[86:89]
	v_mfma_f32_16x16x32_bf16 v[82:85], v[182:185], v[214:217], v[82:85]
	v_mfma_f32_16x16x32_bf16 v[70:73], v[154:157], v[222:225], v[70:73]
	v_mfma_f32_16x16x32_bf16 v[66:69], v[182:185], v[222:225], v[66:69]
	v_mfma_f32_16x16x32_bf16 v[122:125], v[170:173], v[194:197], v[122:125]
	v_mfma_f32_16x16x32_bf16 v[118:121], v[186:189], v[194:197], v[118:121]
	v_mfma_f32_16x16x32_bf16 v[106:109], v[170:173], v[208:211], v[106:109]
	v_mfma_f32_16x16x32_bf16 v[100:103], v[186:189], v[208:211], v[100:103]
	v_mfma_f32_16x16x32_bf16 v[86:89], v[170:173], v[218:221], v[86:89]
	v_mfma_f32_16x16x32_bf16 v[82:85], v[186:189], v[218:221], v[82:85]
	v_mfma_f32_16x16x32_bf16 v[70:73], v[170:173], v[226:229], v[70:73]
	v_mfma_f32_16x16x32_bf16 v[66:69], v[186:189], v[226:229], v[66:69]
	s_barrier
	s_add_i32 s76, s78, s9
	v_lshl_add_u64 v[174:175], s[60:61], 0, v[162:163]
	s_mov_b32 m0, s76
	ds_read_b128 v[190:193], v181 offset:16384
	ds_read_b128 v[194:197], v181 offset:17408
	ds_read_b128 v[204:207], v181 offset:18432
	ds_read_b128 v[208:211], v181 offset:19456
	ds_read_b128 v[214:217], v181 offset:20480
	ds_read_b128 v[218:221], v181 offset:21504
	ds_read_b128 v[222:225], v181 offset:22528
	ds_read_b128 v[226:229], v181 offset:23552
	global_load_lds_dwordx4 v[174:175], off
	s_add_i32 m0, s76, 0x2000
	s_add_u32 s76, s60, 0x40000
	v_lshl_add_u64 v[198:199], s[60:61], 0, v[158:159]
	s_addc_u32 s77, s61, 0
	s_add_i32 s78, s79, s9
	global_load_lds_dwordx4 v[198:199], off
	v_lshl_add_u64 v[104:105], s[76:77], 0, v[162:163]
	s_mov_b32 m0, s78
	v_lshl_add_u64 v[230:231], s[62:63], 0, v[164:165]
	global_load_lds_dwordx4 v[104:105], off
	v_lshl_add_u64 v[104:105], s[76:77], 0, v[158:159]
	s_add_i32 m0, s78, 0x2000
	v_lshl_add_u64 v[232:233], s[62:63], 0, v[160:161]
	global_load_lds_dwordx4 v[104:105], off
	s_mov_b32 m0, s10
	s_nop 0
	global_load_lds_dwordx4 v[230:231], off
	s_mov_b32 m0, s11
	s_nop 0
	global_load_lds_dwordx4 v[232:233], off
	s_waitcnt vmcnt(8)
	s_waitcnt lgkmcnt(0)
	s_barrier
	v_mfma_f32_16x16x32_bf16 v[62:65], v[138:141], v[190:193], v[62:65]
	v_mfma_f32_16x16x32_bf16 v[58:61], v[146:149], v[190:193], v[58:61]
	v_mfma_f32_16x16x32_bf16 v[46:49], v[138:141], v[204:207], v[46:49]
	v_mfma_f32_16x16x32_bf16 v[42:45], v[146:149], v[204:207], v[42:45]
	v_mfma_f32_16x16x32_bf16 v[30:33], v[138:141], v[214:217], v[30:33]
	v_mfma_f32_16x16x32_bf16 v[26:29], v[146:149], v[214:217], v[26:29]
	v_mfma_f32_16x16x32_bf16 v[14:17], v[138:141], v[222:225], v[14:17]
	v_mfma_f32_16x16x32_bf16 v[10:13], v[146:149], v[222:225], v[10:13]
	v_mfma_f32_16x16x32_bf16 v[62:65], v[142:145], v[194:197], v[62:65]
	v_mfma_f32_16x16x32_bf16 v[58:61], v[150:153], v[194:197], v[58:61]
	v_mfma_f32_16x16x32_bf16 v[46:49], v[142:145], v[208:211], v[46:49]
	v_mfma_f32_16x16x32_bf16 v[42:45], v[150:153], v[208:211], v[42:45]
	v_mfma_f32_16x16x32_bf16 v[30:33], v[142:145], v[218:221], v[30:33]
	v_mfma_f32_16x16x32_bf16 v[26:29], v[150:153], v[218:221], v[26:29]
	v_mfma_f32_16x16x32_bf16 v[14:17], v[142:145], v[226:229], v[14:17]
	v_mfma_f32_16x16x32_bf16 v[10:13], v[150:153], v[226:229], v[10:13]
	s_setprio 0
	s_setprio 1
	v_mfma_f32_16x16x32_bf16 v[54:57], v[154:157], v[190:193], v[54:57]
	v_mfma_f32_16x16x32_bf16 v[50:53], v[182:185], v[190:193], v[50:53]
	v_mfma_f32_16x16x32_bf16 v[38:41], v[154:157], v[204:207], v[38:41]
	v_mfma_f32_16x16x32_bf16 v[34:37], v[182:185], v[204:207], v[34:37]
	v_mfma_f32_16x16x32_bf16 v[22:25], v[154:157], v[214:217], v[22:25]
	v_mfma_f32_16x16x32_bf16 v[18:21], v[182:185], v[214:217], v[18:21]
	v_mfma_f32_16x16x32_bf16 v[6:9], v[154:157], v[222:225], v[6:9]
	v_mfma_f32_16x16x32_bf16 v[2:5], v[182:185], v[222:225], v[2:5]
	v_mfma_f32_16x16x32_bf16 v[54:57], v[170:173], v[194:197], v[54:57]
	v_mfma_f32_16x16x32_bf16 v[50:53], v[186:189], v[194:197], v[50:53]
	v_mfma_f32_16x16x32_bf16 v[38:41], v[170:173], v[208:211], v[38:41]
	v_mfma_f32_16x16x32_bf16 v[34:37], v[186:189], v[208:211], v[34:37]
	v_mfma_f32_16x16x32_bf16 v[22:25], v[170:173], v[218:221], v[22:25]
	v_mfma_f32_16x16x32_bf16 v[18:21], v[186:189], v[218:221], v[18:21]
	v_mfma_f32_16x16x32_bf16 v[6:9], v[170:173], v[226:229], v[6:9]
	v_mfma_f32_16x16x32_bf16 v[2:5], v[186:189], v[226:229], v[2:5]
	s_setprio 0
	s_barrier
	s_add_i32 s76, 0, 0x18000
	v_add_u32_e32 v98, s76, v177
	s_add_i32 s77, 0, 0x1c000
	ds_read_b128 v[138:141], v98
	ds_read_b128 v[142:145], v98 offset:1024
	ds_read_b128 v[146:149], v98 offset:2048
	ds_read_b128 v[150:153], v98 offset:3072
	v_add_u32_e32 v98, s77, v177
	ds_read_b128 v[154:157], v98
	ds_read_b128 v[170:173], v98 offset:1024
	ds_read_b128 v[182:185], v98 offset:2048
	ds_read_b128 v[186:189], v98 offset:3072
	s_add_u32 s62, s62, 0x40000
	s_addc_u32 s63, s63, 0
	s_mov_b32 m0, s12
	v_lshl_add_u64 v[104:105], s[62:63], 0, v[164:165]
	ds_read_b128 v[190:193], v181 offset:32768
	ds_read_b128 v[194:197], v181 offset:33792
	ds_read_b128 v[204:207], v181 offset:34816
	ds_read_b128 v[208:211], v181 offset:35840
	ds_read_b128 v[214:217], v181 offset:36864
	ds_read_b128 v[218:221], v181 offset:37888
	ds_read_b128 v[222:225], v181 offset:38912
	ds_read_b128 v[226:229], v181 offset:39936
	s_setprio 1
	global_load_lds_dwordx4 v[104:105], off
	v_lshl_add_u64 v[104:105], s[62:63], 0, v[160:161]
	s_mov_b32 m0, s13
	s_nop 0
	global_load_lds_dwordx4 v[104:105], off
	s_waitcnt vmcnt(8)
	s_waitcnt lgkmcnt(0)
	s_barrier
	v_mfma_f32_16x16x32_bf16 v[130:133], v[138:141], v[190:193], v[130:133]
	v_mfma_f32_16x16x32_bf16 v[126:129], v[146:149], v[190:193], v[126:129]
	v_mfma_f32_16x16x32_bf16 v[114:117], v[138:141], v[204:207], v[114:117]
	v_mfma_f32_16x16x32_bf16 v[110:113], v[146:149], v[204:207], v[110:113]
	v_mfma_f32_16x16x32_bf16 v[94:97], v[138:141], v[214:217], v[94:97]
	v_mfma_f32_16x16x32_bf16 v[90:93], v[146:149], v[214:217], v[90:93]
	v_mfma_f32_16x16x32_bf16 v[78:81], v[138:141], v[222:225], v[78:81]
	v_mfma_f32_16x16x32_bf16 v[74:77], v[146:149], v[222:225], v[74:77]
	v_mfma_f32_16x16x32_bf16 v[130:133], v[142:145], v[194:197], v[130:133]
	v_mfma_f32_16x16x32_bf16 v[126:129], v[150:153], v[194:197], v[126:129]
	v_mfma_f32_16x16x32_bf16 v[114:117], v[142:145], v[208:211], v[114:117]
	v_mfma_f32_16x16x32_bf16 v[110:113], v[150:153], v[208:211], v[110:113]
	v_mfma_f32_16x16x32_bf16 v[94:97], v[142:145], v[218:221], v[94:97]
	v_mfma_f32_16x16x32_bf16 v[90:93], v[150:153], v[218:221], v[90:93]
	v_mfma_f32_16x16x32_bf16 v[78:81], v[142:145], v[226:229], v[78:81]
	v_mfma_f32_16x16x32_bf16 v[74:77], v[150:153], v[226:229], v[74:77]
	s_setprio 0
	s_setprio 1
	v_mfma_f32_16x16x32_bf16 v[122:125], v[154:157], v[190:193], v[122:125]
	v_mfma_f32_16x16x32_bf16 v[118:121], v[182:185], v[190:193], v[118:121]
	v_mfma_f32_16x16x32_bf16 v[104:107], v[154:157], v[204:207], v[106:109]
	v_mfma_f32_16x16x32_bf16 v[100:103], v[182:185], v[204:207], v[100:103]
	v_mfma_f32_16x16x32_bf16 v[86:89], v[154:157], v[214:217], v[86:89]
	v_mfma_f32_16x16x32_bf16 v[82:85], v[182:185], v[214:217], v[82:85]
	v_mfma_f32_16x16x32_bf16 v[70:73], v[154:157], v[222:225], v[70:73]
	v_mfma_f32_16x16x32_bf16 v[66:69], v[182:185], v[222:225], v[66:69]
	v_mfma_f32_16x16x32_bf16 v[122:125], v[170:173], v[194:197], v[122:125]
	v_mfma_f32_16x16x32_bf16 v[118:121], v[186:189], v[194:197], v[118:121]
	v_mfma_f32_16x16x32_bf16 v[106:109], v[170:173], v[208:211], v[104:107]
	v_mfma_f32_16x16x32_bf16 v[102:105], v[186:189], v[208:211], v[100:103]
	v_mfma_f32_16x16x32_bf16 v[86:89], v[170:173], v[218:221], v[86:89]
	v_mfma_f32_16x16x32_bf16 v[82:85], v[186:189], v[218:221], v[82:85]
	v_mfma_f32_16x16x32_bf16 v[70:73], v[170:173], v[226:229], v[70:73]
	v_mfma_f32_16x16x32_bf16 v[66:69], v[186:189], v[226:229], v[66:69]
	s_barrier
	s_add_i32 s62, s76, s9
	v_lshl_add_u64 v[100:101], v[174:175], 0, s[28:29]
	s_mov_b32 m0, s62
	ds_read_b128 v[190:193], v181 offset:49152
	ds_read_b128 v[194:197], v181 offset:50176
	ds_read_b128 v[204:207], v181 offset:51200
	ds_read_b128 v[208:211], v181 offset:52224
	ds_read_b128 v[214:217], v181 offset:53248
	ds_read_b128 v[218:221], v181 offset:54272
	ds_read_b128 v[222:225], v181 offset:55296
	ds_read_b128 v[226:229], v181 offset:56320
	global_load_lds_dwordx4 v[100:101], off
	s_add_i32 m0, s62, 0x2000
	s_add_u32 s60, s60, 0x40080
	v_lshl_add_u64 v[100:101], v[198:199], 0, s[28:29]
	s_addc_u32 s61, s61, 0
	s_add_i32 s62, s77, s9
	global_load_lds_dwordx4 v[100:101], off
	v_lshl_add_u64 v[100:101], s[60:61], 0, v[162:163]
	s_mov_b32 m0, s62
	s_nop 0
	global_load_lds_dwordx4 v[100:101], off
	v_lshl_add_u64 v[100:101], s[60:61], 0, v[158:159]
	s_add_i32 m0, s62, 0x2000
	s_nop 0
	global_load_lds_dwordx4 v[100:101], off
	v_lshl_add_u64 v[100:101], v[230:231], 0, s[28:29]
	s_mov_b32 m0, s16
	s_nop 0
	global_load_lds_dwordx4 v[100:101], off
	v_lshl_add_u64 v[100:101], v[232:233], 0, s[28:29]
	s_mov_b32 m0, s17
	s_nop 0
	global_load_lds_dwordx4 v[100:101], off
	s_waitcnt vmcnt(8)
	s_waitcnt lgkmcnt(0)
	s_barrier
	v_mfma_f32_16x16x32_bf16 v[62:65], v[138:141], v[190:193], v[62:65]
	v_mfma_f32_16x16x32_bf16 v[58:61], v[146:149], v[190:193], v[58:61]
	v_mfma_f32_16x16x32_bf16 v[46:49], v[138:141], v[204:207], v[46:49]
	v_mfma_f32_16x16x32_bf16 v[42:45], v[146:149], v[204:207], v[42:45]
	v_mfma_f32_16x16x32_bf16 v[30:33], v[138:141], v[214:217], v[30:33]
	v_mfma_f32_16x16x32_bf16 v[26:29], v[146:149], v[214:217], v[26:29]
	v_mfma_f32_16x16x32_bf16 v[14:17], v[138:141], v[222:225], v[14:17]
	v_mfma_f32_16x16x32_bf16 v[10:13], v[146:149], v[222:225], v[10:13]
	v_mfma_f32_16x16x32_bf16 v[62:65], v[142:145], v[194:197], v[62:65]
	v_mfma_f32_16x16x32_bf16 v[58:61], v[150:153], v[194:197], v[58:61]
	v_mfma_f32_16x16x32_bf16 v[46:49], v[142:145], v[208:211], v[46:49]
	v_mfma_f32_16x16x32_bf16 v[42:45], v[150:153], v[208:211], v[42:45]
	v_mfma_f32_16x16x32_bf16 v[30:33], v[142:145], v[218:221], v[30:33]
	v_mfma_f32_16x16x32_bf16 v[26:29], v[150:153], v[218:221], v[26:29]
	v_mfma_f32_16x16x32_bf16 v[14:17], v[142:145], v[226:229], v[14:17]
	v_mfma_f32_16x16x32_bf16 v[10:13], v[150:153], v[226:229], v[10:13]
	s_setprio 0
	s_setprio 1
	v_mfma_f32_16x16x32_bf16 v[54:57], v[154:157], v[190:193], v[54:57]
	v_mfma_f32_16x16x32_bf16 v[50:53], v[182:185], v[190:193], v[50:53]
	v_mfma_f32_16x16x32_bf16 v[38:41], v[154:157], v[204:207], v[38:41]
	v_mfma_f32_16x16x32_bf16 v[34:37], v[182:185], v[204:207], v[34:37]
	v_mfma_f32_16x16x32_bf16 v[22:25], v[154:157], v[214:217], v[22:25]
	v_mfma_f32_16x16x32_bf16 v[18:21], v[182:185], v[214:217], v[18:21]
	v_mfma_f32_16x16x32_bf16 v[6:9], v[154:157], v[222:225], v[6:9]
	v_mfma_f32_16x16x32_bf16 v[2:5], v[182:185], v[222:225], v[2:5]
	v_mfma_f32_16x16x32_bf16 v[54:57], v[170:173], v[194:197], v[54:57]
	v_mfma_f32_16x16x32_bf16 v[50:53], v[186:189], v[194:197], v[50:53]
	v_mfma_f32_16x16x32_bf16 v[38:41], v[170:173], v[208:211], v[38:41]
	v_mfma_f32_16x16x32_bf16 v[34:37], v[186:189], v[208:211], v[34:37]
	v_mfma_f32_16x16x32_bf16 v[22:25], v[170:173], v[218:221], v[22:25]
	v_mfma_f32_16x16x32_bf16 v[18:21], v[186:189], v[218:221], v[18:21]
	v_mfma_f32_16x16x32_bf16 v[6:9], v[170:173], v[226:229], v[6:9]
	v_mfma_f32_16x16x32_bf16 v[2:5], v[186:189], v[226:229], v[2:5]
	s_setprio 0
	s_barrier
	s_add_u32 s58, s58, 0x100
	s_addc_u32 s59, s59, 0
	s_cmp_ge_u32 s75, s57
	s_cbranch_scc1 .LBB0_1113

.LBB0_1529:
	s_add_u32 s50, s48, 0x100
	s_addc_u32 s51, s49, 0
	s_add_i32 s58, 0, 0x10000
	s_cmp_eq_u32 s57, 40
	s_cselect_b32 s55, s1, s51
	s_cselect_b32 s54, s0, s50
	s_cselect_b32 s53, s47, s56
	s_cselect_b32 s52, s46, s33
	s_add_i32 s59, 0, 0x14000
	v_add_u32_e32 v144, s58, v186
	v_add_u32_e32 v160, s59, v186
	ds_read_b128 v[132:135], v144
	ds_read_b128 v[136:139], v144 offset:1024
	ds_read_b128 v[140:143], v144 offset:2048
	ds_read_b128 v[144:147], v144 offset:3072
	ds_read_b128 v[148:151], v160
	ds_read_b128 v[152:155], v160 offset:1024
	ds_read_b128 v[156:159], v160 offset:2048
	ds_read_b128 v[160:163], v160 offset:3072
	v_lshl_add_u64 v[214:215], s[48:49], 0, v[174:175]
	s_add_i32 m0, s4, 0xc000
	ds_read_b128 v[164:167], v187
	ds_read_b128 v[178:181], v187 offset:1024
	ds_read_b128 v[182:185], v187 offset:2048
	ds_read_b128 v[188:191], v187 offset:3072
	ds_read_b128 v[192:195], v187 offset:4096
	ds_read_b128 v[196:199], v187 offset:5120
	ds_read_b128 v[204:207], v187 offset:6144
	ds_read_b128 v[208:211], v187 offset:7168
	s_setprio 1
	global_load_lds_dwordx4 v[214:215], off
	v_lshl_add_u64 v[214:215], s[48:49], 0, v[176:177]
	s_add_i32 m0, s4, 0xe000
	s_nop 0
	global_load_lds_dwordx4 v[214:215], off
	s_waitcnt vmcnt(8)
	s_waitcnt lgkmcnt(0)
	s_barrier
	v_mfma_f32_16x16x32_bf16 v[128:131], v[132:135], v[164:167], v[128:131]
	v_mfma_f32_16x16x32_bf16 v[124:127], v[140:143], v[164:167], v[124:127]
	v_mfma_f32_16x16x32_bf16 v[120:123], v[132:135], v[182:185], v[120:123]
	v_mfma_f32_16x16x32_bf16 v[116:119], v[140:143], v[182:185], v[116:119]
	v_mfma_f32_16x16x32_bf16 v[112:115], v[132:135], v[192:195], v[112:115]
	v_mfma_f32_16x16x32_bf16 v[108:111], v[140:143], v[192:195], v[108:111]
	v_mfma_f32_16x16x32_bf16 v[104:107], v[132:135], v[204:207], v[104:107]
	v_mfma_f32_16x16x32_bf16 v[100:103], v[140:143], v[204:207], v[100:103]
	v_mfma_f32_16x16x32_bf16 v[128:131], v[136:139], v[178:181], v[128:131]
	v_mfma_f32_16x16x32_bf16 v[124:127], v[144:147], v[178:181], v[124:127]
	v_mfma_f32_16x16x32_bf16 v[120:123], v[136:139], v[188:191], v[120:123]
	v_mfma_f32_16x16x32_bf16 v[116:119], v[144:147], v[188:191], v[116:119]
	v_mfma_f32_16x16x32_bf16 v[112:115], v[136:139], v[196:199], v[112:115]
	v_mfma_f32_16x16x32_bf16 v[108:111], v[144:147], v[196:199], v[108:111]
	v_mfma_f32_16x16x32_bf16 v[104:107], v[136:139], v[208:211], v[104:107]
	v_mfma_f32_16x16x32_bf16 v[100:103], v[144:147], v[208:211], v[100:103]
	s_setprio 0
	s_setprio 1
	v_mfma_f32_16x16x32_bf16 v[62:65], v[148:151], v[164:167], v[62:65]
	v_mfma_f32_16x16x32_bf16 v[58:61], v[156:159], v[164:167], v[58:61]
	v_mfma_f32_16x16x32_bf16 v[54:57], v[148:151], v[182:185], v[54:57]
	v_mfma_f32_16x16x32_bf16 v[50:53], v[156:159], v[182:185], v[50:53]
	v_mfma_f32_16x16x32_bf16 v[46:49], v[148:151], v[192:195], v[46:49]
	v_mfma_f32_16x16x32_bf16 v[42:45], v[156:159], v[192:195], v[42:45]
	v_mfma_f32_16x16x32_bf16 v[38:41], v[148:151], v[204:207], v[38:41]
	v_mfma_f32_16x16x32_bf16 v[34:37], v[156:159], v[204:207], v[34:37]
	v_mfma_f32_16x16x32_bf16 v[62:65], v[152:155], v[178:181], v[62:65]
	v_mfma_f32_16x16x32_bf16 v[58:61], v[160:163], v[178:181], v[58:61]
	v_mfma_f32_16x16x32_bf16 v[54:57], v[152:155], v[188:191], v[54:57]
	v_mfma_f32_16x16x32_bf16 v[50:53], v[160:163], v[188:191], v[50:53]
	v_mfma_f32_16x16x32_bf16 v[46:49], v[152:155], v[196:199], v[46:49]
	v_mfma_f32_16x16x32_bf16 v[42:45], v[160:163], v[196:199], v[42:45]
	v_mfma_f32_16x16x32_bf16 v[38:41], v[152:155], v[208:211], v[38:41]
	v_mfma_f32_16x16x32_bf16 v[34:37], v[160:163], v[208:211], v[34:37]
	s_barrier
	s_add_i32 s48, s58, s2
	v_lshl_add_u64 v[214:215], s[52:53], 0, v[98:99]
	s_mov_b32 m0, s48
	ds_read_b128 v[164:167], v187 offset:16384
	ds_read_b128 v[178:181], v187 offset:17408
	ds_read_b128 v[182:185], v187 offset:18432
	ds_read_b128 v[188:191], v187 offset:19456
	ds_read_b128 v[192:195], v187 offset:20480
	ds_read_b128 v[196:199], v187 offset:21504
	ds_read_b128 v[204:207], v187 offset:22528
	ds_read_b128 v[208:211], v187 offset:23552
	global_load_lds_dwordx4 v[214:215], off
	s_add_i32 m0, s48, 0x2000
	s_add_u32 s48, s52, 0xb0000
	v_lshl_add_u64 v[216:217], s[52:53], 0, v[168:169]
	s_addc_u32 s49, s53, 0
	s_add_i32 s58, s59, s2
	global_load_lds_dwordx4 v[216:217], off
	v_lshl_add_u64 v[218:219], s[48:49], 0, v[98:99]
	s_mov_b32 m0, s58
	v_lshl_add_u64 v[220:221], s[54:55], 0, v[170:171]
	global_load_lds_dwordx4 v[218:219], off
	v_lshl_add_u64 v[218:219], s[48:49], 0, v[168:169]
	s_add_i32 m0, s58, 0x2000
	s_nop 0
	global_load_lds_dwordx4 v[218:219], off
	v_lshl_add_u64 v[218:219], s[54:55], 0, v[172:173]
	s_mov_b32 m0, s4
	s_nop 0
	global_load_lds_dwordx4 v[218:219], off
	s_mov_b32 m0, s7
	s_nop 0
	global_load_lds_dwordx4 v[220:221], off
	s_waitcnt vmcnt(8)
	s_waitcnt lgkmcnt(0)
	s_barrier
	v_mfma_f32_16x16x32_bf16 v[94:97], v[132:135], v[164:167], v[94:97]
	v_mfma_f32_16x16x32_bf16 v[90:93], v[140:143], v[164:167], v[90:93]
	v_mfma_f32_16x16x32_bf16 v[86:89], v[132:135], v[182:185], v[86:89]
	v_mfma_f32_16x16x32_bf16 v[82:85], v[140:143], v[182:185], v[82:85]
	v_mfma_f32_16x16x32_bf16 v[78:81], v[132:135], v[192:195], v[78:81]
	v_mfma_f32_16x16x32_bf16 v[74:77], v[140:143], v[192:195], v[74:77]
	v_mfma_f32_16x16x32_bf16 v[70:73], v[132:135], v[204:207], v[70:73]
	v_mfma_f32_16x16x32_bf16 v[66:69], v[140:143], v[204:207], v[66:69]
	v_mfma_f32_16x16x32_bf16 v[94:97], v[136:139], v[178:181], v[94:97]
	v_mfma_f32_16x16x32_bf16 v[90:93], v[144:147], v[178:181], v[90:93]
	v_mfma_f32_16x16x32_bf16 v[86:89], v[136:139], v[188:191], v[86:89]
	v_mfma_f32_16x16x32_bf16 v[82:85], v[144:147], v[188:191], v[82:85]
	v_mfma_f32_16x16x32_bf16 v[78:81], v[136:139], v[196:199], v[78:81]
	v_mfma_f32_16x16x32_bf16 v[74:77], v[144:147], v[196:199], v[74:77]
	v_mfma_f32_16x16x32_bf16 v[70:73], v[136:139], v[208:211], v[70:73]
	v_mfma_f32_16x16x32_bf16 v[66:69], v[144:147], v[208:211], v[66:69]
	s_setprio 0
	s_setprio 1
	v_mfma_f32_16x16x32_bf16 v[30:33], v[148:151], v[164:167], v[30:33]
	v_mfma_f32_16x16x32_bf16 v[26:29], v[156:159], v[164:167], v[26:29]
	v_mfma_f32_16x16x32_bf16 v[22:25], v[148:151], v[182:185], v[22:25]
	v_mfma_f32_16x16x32_bf16 v[18:21], v[156:159], v[182:185], v[18:21]
	v_mfma_f32_16x16x32_bf16 v[14:17], v[148:151], v[192:195], v[14:17]
	v_mfma_f32_16x16x32_bf16 v[10:13], v[156:159], v[192:195], v[10:13]
	v_mfma_f32_16x16x32_bf16 v[6:9], v[148:151], v[204:207], v[6:9]
	v_mfma_f32_16x16x32_bf16 v[2:5], v[156:159], v[204:207], v[2:5]
	v_mfma_f32_16x16x32_bf16 v[30:33], v[152:155], v[178:181], v[30:33]
	v_mfma_f32_16x16x32_bf16 v[26:29], v[160:163], v[178:181], v[26:29]
	v_mfma_f32_16x16x32_bf16 v[22:25], v[152:155], v[188:191], v[22:25]
	v_mfma_f32_16x16x32_bf16 v[18:21], v[160:163], v[188:191], v[18:21]
	v_mfma_f32_16x16x32_bf16 v[14:17], v[152:155], v[196:199], v[14:17]
	v_mfma_f32_16x16x32_bf16 v[10:13], v[160:163], v[196:199], v[10:13]
	v_mfma_f32_16x16x32_bf16 v[6:9], v[152:155], v[208:211], v[6:9]
	v_mfma_f32_16x16x32_bf16 v[2:5], v[160:163], v[208:211], v[2:5]
	s_setprio 0
	s_barrier
	s_add_i32 s58, 0, 0x18000
	s_add_i32 s59, 0, 0x1c000
	v_add_u32_e32 v144, s58, v186
	v_add_u32_e32 v160, s59, v186
	ds_read_b128 v[132:135], v144
	ds_read_b128 v[136:139], v144 offset:1024
	ds_read_b128 v[140:143], v144 offset:2048
	ds_read_b128 v[144:147], v144 offset:3072
	ds_read_b128 v[148:151], v160
	ds_read_b128 v[152:155], v160 offset:1024
	ds_read_b128 v[156:159], v160 offset:2048
	ds_read_b128 v[160:163], v160 offset:3072
	s_add_u32 s48, s54, 0xb0000
	s_addc_u32 s49, s55, 0
	s_mov_b32 m0, s8
	v_lshl_add_u64 v[222:223], s[48:49], 0, v[172:173]
	ds_read_b128 v[164:167], v187 offset:32768
	ds_read_b128 v[178:181], v187 offset:33792
	ds_read_b128 v[182:185], v187 offset:34816
	ds_read_b128 v[188:191], v187 offset:35840
	ds_read_b128 v[192:195], v187 offset:36864
	ds_read_b128 v[196:199], v187 offset:37888
	ds_read_b128 v[204:207], v187 offset:38912
	ds_read_b128 v[208:211], v187 offset:39936
	s_setprio 1
	global_load_lds_dwordx4 v[222:223], off
	v_lshl_add_u64 v[222:223], s[48:49], 0, v[170:171]
	s_mov_b32 m0, s9
	s_nop 0
	global_load_lds_dwordx4 v[222:223], off
	s_waitcnt vmcnt(8)
	s_waitcnt lgkmcnt(0)
	s_barrier
	v_mfma_f32_16x16x32_bf16 v[128:131], v[132:135], v[164:167], v[128:131]
	v_mfma_f32_16x16x32_bf16 v[124:127], v[140:143], v[164:167], v[124:127]
	v_mfma_f32_16x16x32_bf16 v[120:123], v[132:135], v[182:185], v[120:123]
	v_mfma_f32_16x16x32_bf16 v[116:119], v[140:143], v[182:185], v[116:119]
	v_mfma_f32_16x16x32_bf16 v[112:115], v[132:135], v[192:195], v[112:115]
	v_mfma_f32_16x16x32_bf16 v[108:111], v[140:143], v[192:195], v[108:111]
	v_mfma_f32_16x16x32_bf16 v[104:107], v[132:135], v[204:207], v[104:107]
	v_mfma_f32_16x16x32_bf16 v[100:103], v[140:143], v[204:207], v[100:103]
	v_mfma_f32_16x16x32_bf16 v[128:131], v[136:139], v[178:181], v[128:131]
	v_mfma_f32_16x16x32_bf16 v[124:127], v[144:147], v[178:181], v[124:127]
	v_mfma_f32_16x16x32_bf16 v[120:123], v[136:139], v[188:191], v[120:123]
	v_mfma_f32_16x16x32_bf16 v[116:119], v[144:147], v[188:191], v[116:119]
	v_mfma_f32_16x16x32_bf16 v[112:115], v[136:139], v[196:199], v[112:115]
	v_mfma_f32_16x16x32_bf16 v[108:111], v[144:147], v[196:199], v[108:111]
	v_mfma_f32_16x16x32_bf16 v[104:107], v[136:139], v[208:211], v[104:107]
	v_mfma_f32_16x16x32_bf16 v[100:103], v[144:147], v[208:211], v[100:103]
	s_setprio 0
	s_setprio 1
	v_mfma_f32_16x16x32_bf16 v[62:65], v[148:151], v[164:167], v[62:65]
	v_mfma_f32_16x16x32_bf16 v[58:61], v[156:159], v[164:167], v[58:61]
	v_mfma_f32_16x16x32_bf16 v[54:57], v[148:151], v[182:185], v[54:57]
	v_mfma_f32_16x16x32_bf16 v[50:53], v[156:159], v[182:185], v[50:53]
	v_mfma_f32_16x16x32_bf16 v[46:49], v[148:151], v[192:195], v[46:49]
	v_mfma_f32_16x16x32_bf16 v[42:45], v[156:159], v[192:195], v[42:45]
	v_mfma_f32_16x16x32_bf16 v[38:41], v[148:151], v[204:207], v[38:41]
	v_mfma_f32_16x16x32_bf16 v[34:37], v[156:159], v[204:207], v[34:37]
	v_mfma_f32_16x16x32_bf16 v[62:65], v[152:155], v[178:181], v[62:65]
	v_mfma_f32_16x16x32_bf16 v[58:61], v[160:163], v[178:181], v[58:61]
	v_mfma_f32_16x16x32_bf16 v[54:57], v[152:155], v[188:191], v[54:57]
	v_mfma_f32_16x16x32_bf16 v[50:53], v[160:163], v[188:191], v[50:53]
	v_mfma_f32_16x16x32_bf16 v[46:49], v[152:155], v[196:199], v[46:49]
	v_mfma_f32_16x16x32_bf16 v[42:45], v[160:163], v[196:199], v[42:45]
	v_mfma_f32_16x16x32_bf16 v[38:41], v[152:155], v[208:211], v[38:41]
	v_mfma_f32_16x16x32_bf16 v[34:37], v[160:163], v[208:211], v[34:37]
	s_barrier
	s_add_i32 s48, s58, s2
	v_lshl_add_u64 v[214:215], v[214:215], 0, s[28:29]
	s_mov_b32 m0, s48
	ds_read_b128 v[164:167], v187 offset:49152
	ds_read_b128 v[178:181], v187 offset:50176
	ds_read_b128 v[182:185], v187 offset:51200
	ds_read_b128 v[188:191], v187 offset:52224
	ds_read_b128 v[192:195], v187 offset:53248
	ds_read_b128 v[196:199], v187 offset:54272
	ds_read_b128 v[204:207], v187 offset:55296
	ds_read_b128 v[208:211], v187 offset:56320
	global_load_lds_dwordx4 v[214:215], off
	s_add_i32 m0, s48, 0x2000
	s_add_u32 s48, s52, 0xb0080
	v_lshl_add_u64 v[214:215], v[216:217], 0, s[28:29]
	s_addc_u32 s49, s53, 0
	s_add_i32 s52, s59, s2
	global_load_lds_dwordx4 v[214:215], off
	v_lshl_add_u64 v[214:215], s[48:49], 0, v[98:99]
	s_mov_b32 m0, s52
	s_nop 0
	global_load_lds_dwordx4 v[214:215], off
	v_lshl_add_u64 v[214:215], s[48:49], 0, v[168:169]
	s_add_i32 m0, s52, 0x2000
	s_nop 0
	global_load_lds_dwordx4 v[214:215], off
	v_lshl_add_u64 v[214:215], v[218:219], 0, s[28:29]
	s_mov_b32 m0, s12
	s_nop 0
	global_load_lds_dwordx4 v[214:215], off
	v_lshl_add_u64 v[214:215], v[220:221], 0, s[28:29]
	s_mov_b32 m0, s13
	s_nop 0
	global_load_lds_dwordx4 v[214:215], off
	s_waitcnt vmcnt(8)
	s_waitcnt lgkmcnt(0)
	s_barrier
	v_mfma_f32_16x16x32_bf16 v[94:97], v[132:135], v[164:167], v[94:97]
	v_mfma_f32_16x16x32_bf16 v[90:93], v[140:143], v[164:167], v[90:93]
	v_mfma_f32_16x16x32_bf16 v[86:89], v[132:135], v[182:185], v[86:89]
	v_mfma_f32_16x16x32_bf16 v[82:85], v[140:143], v[182:185], v[82:85]
	v_mfma_f32_16x16x32_bf16 v[78:81], v[132:135], v[192:195], v[78:81]
	v_mfma_f32_16x16x32_bf16 v[74:77], v[140:143], v[192:195], v[74:77]
	v_mfma_f32_16x16x32_bf16 v[70:73], v[132:135], v[204:207], v[70:73]
	v_mfma_f32_16x16x32_bf16 v[66:69], v[140:143], v[204:207], v[66:69]
	v_mfma_f32_16x16x32_bf16 v[94:97], v[136:139], v[178:181], v[94:97]
	v_mfma_f32_16x16x32_bf16 v[90:93], v[144:147], v[178:181], v[90:93]
	v_mfma_f32_16x16x32_bf16 v[86:89], v[136:139], v[188:191], v[86:89]
	v_mfma_f32_16x16x32_bf16 v[82:85], v[144:147], v[188:191], v[82:85]
	v_mfma_f32_16x16x32_bf16 v[78:81], v[136:139], v[196:199], v[78:81]
	v_mfma_f32_16x16x32_bf16 v[74:77], v[144:147], v[196:199], v[74:77]
	v_mfma_f32_16x16x32_bf16 v[70:73], v[136:139], v[208:211], v[70:73]
	v_mfma_f32_16x16x32_bf16 v[66:69], v[144:147], v[208:211], v[66:69]
	s_setprio 0
	s_setprio 1
	v_mfma_f32_16x16x32_bf16 v[30:33], v[148:151], v[164:167], v[30:33]
	v_mfma_f32_16x16x32_bf16 v[26:29], v[156:159], v[164:167], v[26:29]
	v_mfma_f32_16x16x32_bf16 v[22:25], v[148:151], v[182:185], v[22:25]
	v_mfma_f32_16x16x32_bf16 v[18:21], v[156:159], v[182:185], v[18:21]
	v_mfma_f32_16x16x32_bf16 v[14:17], v[148:151], v[192:195], v[14:17]
	v_mfma_f32_16x16x32_bf16 v[10:13], v[156:159], v[192:195], v[10:13]
	v_mfma_f32_16x16x32_bf16 v[6:9], v[148:151], v[204:207], v[6:9]
	v_mfma_f32_16x16x32_bf16 v[2:5], v[156:159], v[204:207], v[2:5]
	v_mfma_f32_16x16x32_bf16 v[30:33], v[152:155], v[178:181], v[30:33]
	v_mfma_f32_16x16x32_bf16 v[26:29], v[160:163], v[178:181], v[26:29]
	v_mfma_f32_16x16x32_bf16 v[22:25], v[152:155], v[188:191], v[22:25]
	v_mfma_f32_16x16x32_bf16 v[18:21], v[160:163], v[188:191], v[18:21]
	v_mfma_f32_16x16x32_bf16 v[14:17], v[152:155], v[196:199], v[14:17]
	v_mfma_f32_16x16x32_bf16 v[10:13], v[160:163], v[196:199], v[10:13]
	v_mfma_f32_16x16x32_bf16 v[6:9], v[152:155], v[208:211], v[6:9]
	v_mfma_f32_16x16x32_bf16 v[2:5], v[160:163], v[208:211], v[2:5]
	s_setprio 0
	s_barrier
	s_add_i32 s57, s57, 2
	s_add_u32 s33, s33, 0x100
	s_addc_u32 s56, s56, 0
	s_cmp_gt_u32 s57, 41
	s_mov_b64 s[48:49], s[50:51]
	s_cbranch_scc0 .LBB0_1529
	s_and_b64 vcc, exec, s[44:45]
	s_cbranch_vccz .LBB0_1532
	s_barrier

.LBB0_1553:
	s_add_i32 s63, s54, 2
	s_add_u32 s52, s50, 0x100
	s_addc_u32 s53, s51, 0
	s_add_i32 s64, 0, 0x10000
	s_cmp_eq_u32 s60, s54
	s_cselect_b32 s57, s45, s53
	s_cselect_b32 s56, s44, s52
	s_cselect_b32 s55, s47, s62
	s_cselect_b32 s54, s46, s61
	s_add_i32 s65, 0, 0x14000
	v_add_u32_e32 v144, s64, v198
	v_add_u32_e32 v160, s65, v198
	s_waitcnt lgkmcnt(0)
	ds_read_b128 v[132:135], v144
	ds_read_b128 v[136:139], v144 offset:1024
	ds_read_b128 v[140:143], v144 offset:2048
	ds_read_b128 v[144:147], v144 offset:3072
	ds_read_b128 v[148:151], v160
	ds_read_b128 v[152:155], v160 offset:1024
	ds_read_b128 v[156:159], v160 offset:2048
	ds_read_b128 v[160:163], v160 offset:3072
	v_lshl_add_u64 v[214:215], s[50:51], 0, v[178:179]
	s_add_i32 m0, s4, 0xc000
	ds_read_b128 v[164:167], v199
	ds_read_b128 v[168:171], v199 offset:1024
	ds_read_b128 v[182:185], v199 offset:2048
	ds_read_b128 v[186:189], v199 offset:3072
	ds_read_b128 v[190:193], v199 offset:4096
	ds_read_b128 v[194:197], v199 offset:5120
	ds_read_b128 v[204:207], v199 offset:6144
	ds_read_b128 v[208:211], v199 offset:7168
	s_setprio 1
	global_load_lds_dwordx4 v[214:215], off
	v_lshl_add_u64 v[214:215], s[50:51], 0, v[180:181]
	s_add_i32 m0, s4, 0xe000
	s_nop 0
	global_load_lds_dwordx4 v[214:215], off
	s_waitcnt vmcnt(8)
	s_waitcnt lgkmcnt(0)
	s_barrier
	v_mfma_f32_16x16x32_bf16 v[128:131], v[132:135], v[164:167], v[128:131]
	v_mfma_f32_16x16x32_bf16 v[124:127], v[140:143], v[164:167], v[124:127]
	v_mfma_f32_16x16x32_bf16 v[120:123], v[132:135], v[182:185], v[120:123]
	v_mfma_f32_16x16x32_bf16 v[116:119], v[140:143], v[182:185], v[116:119]
	v_mfma_f32_16x16x32_bf16 v[104:107], v[132:135], v[190:193], v[104:107]
	v_mfma_f32_16x16x32_bf16 v[100:103], v[140:143], v[190:193], v[100:103]
	v_mfma_f32_16x16x32_bf16 v[86:89], v[132:135], v[204:207], v[86:89]
	v_mfma_f32_16x16x32_bf16 v[82:85], v[140:143], v[204:207], v[82:85]
	v_mfma_f32_16x16x32_bf16 v[128:131], v[136:139], v[168:171], v[128:131]
	v_mfma_f32_16x16x32_bf16 v[124:127], v[144:147], v[168:171], v[124:127]
	v_mfma_f32_16x16x32_bf16 v[120:123], v[136:139], v[186:189], v[120:123]
	v_mfma_f32_16x16x32_bf16 v[116:119], v[144:147], v[186:189], v[116:119]
	v_mfma_f32_16x16x32_bf16 v[104:107], v[136:139], v[194:197], v[104:107]
	v_mfma_f32_16x16x32_bf16 v[100:103], v[144:147], v[194:197], v[100:103]
	v_mfma_f32_16x16x32_bf16 v[86:89], v[136:139], v[208:211], v[86:89]
	v_mfma_f32_16x16x32_bf16 v[82:85], v[144:147], v[208:211], v[82:85]
	s_setprio 0
	s_setprio 1
	v_mfma_f32_16x16x32_bf16 v[112:115], v[148:151], v[164:167], v[112:115]
	v_mfma_f32_16x16x32_bf16 v[108:111], v[156:159], v[164:167], v[108:111]
	v_mfma_f32_16x16x32_bf16 v[94:97], v[148:151], v[182:185], v[94:97]
	v_mfma_f32_16x16x32_bf16 v[90:93], v[156:159], v[182:185], v[90:93]
	v_mfma_f32_16x16x32_bf16 v[78:81], v[148:151], v[190:193], v[78:81]
	v_mfma_f32_16x16x32_bf16 v[74:77], v[156:159], v[190:193], v[74:77]
	v_mfma_f32_16x16x32_bf16 v[70:73], v[148:151], v[204:207], v[70:73]
	v_mfma_f32_16x16x32_bf16 v[66:69], v[156:159], v[204:207], v[66:69]
	v_mfma_f32_16x16x32_bf16 v[112:115], v[152:155], v[168:171], v[112:115]
	v_mfma_f32_16x16x32_bf16 v[108:111], v[160:163], v[168:171], v[108:111]
	v_mfma_f32_16x16x32_bf16 v[94:97], v[152:155], v[186:189], v[94:97]
	v_mfma_f32_16x16x32_bf16 v[90:93], v[160:163], v[186:189], v[90:93]
	v_mfma_f32_16x16x32_bf16 v[78:81], v[152:155], v[194:197], v[78:81]
	v_mfma_f32_16x16x32_bf16 v[74:77], v[160:163], v[194:197], v[74:77]
	v_mfma_f32_16x16x32_bf16 v[70:73], v[152:155], v[208:211], v[70:73]
	v_mfma_f32_16x16x32_bf16 v[66:69], v[160:163], v[208:211], v[66:69]
	s_barrier
	s_add_i32 s50, s64, s2
	v_lshl_add_u64 v[214:215], s[54:55], 0, v[98:99]
	s_mov_b32 m0, s50
	ds_read_b128 v[164:167], v199 offset:16384
	ds_read_b128 v[168:171], v199 offset:17408
	ds_read_b128 v[182:185], v199 offset:18432
	ds_read_b128 v[186:189], v199 offset:19456
	ds_read_b128 v[190:193], v199 offset:20480
	ds_read_b128 v[194:197], v199 offset:21504
	ds_read_b128 v[204:207], v199 offset:22528
	ds_read_b128 v[208:211], v199 offset:23552
	global_load_lds_dwordx4 v[214:215], off
	s_add_i32 m0, s50, 0x2000
	s_add_u32 s50, s54, 0xb0000
	v_lshl_add_u64 v[216:217], s[54:55], 0, v[172:173]
	s_addc_u32 s51, s55, 0
	s_add_i32 s64, s65, s2
	global_load_lds_dwordx4 v[216:217], off
	v_lshl_add_u64 v[218:219], s[50:51], 0, v[98:99]
	s_mov_b32 m0, s64
	v_lshl_add_u64 v[220:221], s[56:57], 0, v[174:175]
	global_load_lds_dwordx4 v[218:219], off
	v_lshl_add_u64 v[218:219], s[50:51], 0, v[172:173]
	s_add_i32 m0, s64, 0x2000
	s_nop 0
	global_load_lds_dwordx4 v[218:219], off
	v_lshl_add_u64 v[218:219], s[56:57], 0, v[176:177]
	s_mov_b32 m0, s4
	s_nop 0
	global_load_lds_dwordx4 v[218:219], off
	s_mov_b32 m0, s7
	s_nop 0
	global_load_lds_dwordx4 v[220:221], off
	s_waitcnt vmcnt(8)
	s_waitcnt lgkmcnt(0)
	s_barrier
	v_mfma_f32_16x16x32_bf16 v[62:65], v[132:135], v[164:167], v[62:65]
	v_mfma_f32_16x16x32_bf16 v[58:61], v[140:143], v[164:167], v[58:61]
	v_mfma_f32_16x16x32_bf16 v[54:57], v[132:135], v[182:185], v[54:57]
	v_mfma_f32_16x16x32_bf16 v[50:53], v[140:143], v[182:185], v[50:53]
	v_mfma_f32_16x16x32_bf16 v[38:41], v[132:135], v[190:193], v[38:41]
	v_mfma_f32_16x16x32_bf16 v[34:37], v[140:143], v[190:193], v[34:37]
	v_mfma_f32_16x16x32_bf16 v[22:25], v[132:135], v[204:207], v[22:25]
	v_mfma_f32_16x16x32_bf16 v[18:21], v[140:143], v[204:207], v[18:21]
	v_mfma_f32_16x16x32_bf16 v[62:65], v[136:139], v[168:171], v[62:65]
	v_mfma_f32_16x16x32_bf16 v[58:61], v[144:147], v[168:171], v[58:61]
	v_mfma_f32_16x16x32_bf16 v[54:57], v[136:139], v[186:189], v[54:57]
	v_mfma_f32_16x16x32_bf16 v[50:53], v[144:147], v[186:189], v[50:53]
	v_mfma_f32_16x16x32_bf16 v[38:41], v[136:139], v[194:197], v[38:41]
	v_mfma_f32_16x16x32_bf16 v[34:37], v[144:147], v[194:197], v[34:37]
	v_mfma_f32_16x16x32_bf16 v[22:25], v[136:139], v[208:211], v[22:25]
	v_mfma_f32_16x16x32_bf16 v[18:21], v[144:147], v[208:211], v[18:21]
	s_setprio 0
	s_setprio 1
	v_mfma_f32_16x16x32_bf16 v[46:49], v[148:151], v[164:167], v[46:49]
	v_mfma_f32_16x16x32_bf16 v[42:45], v[156:159], v[164:167], v[42:45]
	v_mfma_f32_16x16x32_bf16 v[30:33], v[148:151], v[182:185], v[30:33]
	v_mfma_f32_16x16x32_bf16 v[26:29], v[156:159], v[182:185], v[26:29]
	v_mfma_f32_16x16x32_bf16 v[14:17], v[148:151], v[190:193], v[14:17]
	v_mfma_f32_16x16x32_bf16 v[10:13], v[156:159], v[190:193], v[10:13]
	v_mfma_f32_16x16x32_bf16 v[6:9], v[148:151], v[204:207], v[6:9]
	v_mfma_f32_16x16x32_bf16 v[2:5], v[156:159], v[204:207], v[2:5]
	v_mfma_f32_16x16x32_bf16 v[46:49], v[152:155], v[168:171], v[46:49]
	v_mfma_f32_16x16x32_bf16 v[42:45], v[160:163], v[168:171], v[42:45]
	v_mfma_f32_16x16x32_bf16 v[30:33], v[152:155], v[186:189], v[30:33]
	v_mfma_f32_16x16x32_bf16 v[26:29], v[160:163], v[186:189], v[26:29]
	v_mfma_f32_16x16x32_bf16 v[14:17], v[152:155], v[194:197], v[14:17]
	v_mfma_f32_16x16x32_bf16 v[10:13], v[160:163], v[194:197], v[10:13]
	v_mfma_f32_16x16x32_bf16 v[6:9], v[152:155], v[208:211], v[6:9]
	v_mfma_f32_16x16x32_bf16 v[2:5], v[160:163], v[208:211], v[2:5]
	s_setprio 0
	s_barrier
	s_add_i32 s64, 0, 0x18000
	s_add_i32 s65, 0, 0x1c000
	v_add_u32_e32 v144, s64, v198
	v_add_u32_e32 v160, s65, v198
	ds_read_b128 v[132:135], v144
	ds_read_b128 v[136:139], v144 offset:1024
	ds_read_b128 v[140:143], v144 offset:2048
	ds_read_b128 v[144:147], v144 offset:3072
	ds_read_b128 v[148:151], v160
	ds_read_b128 v[152:155], v160 offset:1024
	ds_read_b128 v[156:159], v160 offset:2048
	ds_read_b128 v[160:163], v160 offset:3072
	s_add_u32 s50, s56, 0xb0000
	s_addc_u32 s51, s57, 0
	s_mov_b32 m0, s8
	v_lshl_add_u64 v[222:223], s[50:51], 0, v[176:177]
	ds_read_b128 v[164:167], v199 offset:32768
	ds_read_b128 v[168:171], v199 offset:33792
	ds_read_b128 v[182:185], v199 offset:34816
	ds_read_b128 v[186:189], v199 offset:35840
	ds_read_b128 v[190:193], v199 offset:36864
	ds_read_b128 v[194:197], v199 offset:37888
	ds_read_b128 v[204:207], v199 offset:38912
	ds_read_b128 v[208:211], v199 offset:39936
	s_setprio 1
	global_load_lds_dwordx4 v[222:223], off
	v_lshl_add_u64 v[222:223], s[50:51], 0, v[174:175]
	s_mov_b32 m0, s9
	s_nop 0
	global_load_lds_dwordx4 v[222:223], off
	s_waitcnt vmcnt(8)
	s_waitcnt lgkmcnt(0)
	s_barrier
	v_mfma_f32_16x16x32_bf16 v[128:131], v[132:135], v[164:167], v[128:131]
	v_mfma_f32_16x16x32_bf16 v[124:127], v[140:143], v[164:167], v[124:127]
	v_mfma_f32_16x16x32_bf16 v[120:123], v[132:135], v[182:185], v[120:123]
	v_mfma_f32_16x16x32_bf16 v[116:119], v[140:143], v[182:185], v[116:119]
	v_mfma_f32_16x16x32_bf16 v[104:107], v[132:135], v[190:193], v[104:107]
	v_mfma_f32_16x16x32_bf16 v[100:103], v[140:143], v[190:193], v[100:103]
	v_mfma_f32_16x16x32_bf16 v[86:89], v[132:135], v[204:207], v[86:89]
	v_mfma_f32_16x16x32_bf16 v[82:85], v[140:143], v[204:207], v[82:85]
	v_mfma_f32_16x16x32_bf16 v[128:131], v[136:139], v[168:171], v[128:131]
	v_mfma_f32_16x16x32_bf16 v[124:127], v[144:147], v[168:171], v[124:127]
	v_mfma_f32_16x16x32_bf16 v[120:123], v[136:139], v[186:189], v[120:123]
	v_mfma_f32_16x16x32_bf16 v[116:119], v[144:147], v[186:189], v[116:119]
	v_mfma_f32_16x16x32_bf16 v[104:107], v[136:139], v[194:197], v[104:107]
	v_mfma_f32_16x16x32_bf16 v[100:103], v[144:147], v[194:197], v[100:103]
	v_mfma_f32_16x16x32_bf16 v[86:89], v[136:139], v[208:211], v[86:89]
	v_mfma_f32_16x16x32_bf16 v[82:85], v[144:147], v[208:211], v[82:85]
	s_setprio 0
	s_setprio 1
	v_mfma_f32_16x16x32_bf16 v[112:115], v[148:151], v[164:167], v[112:115]
	v_mfma_f32_16x16x32_bf16 v[108:111], v[156:159], v[164:167], v[108:111]
	v_mfma_f32_16x16x32_bf16 v[94:97], v[148:151], v[182:185], v[94:97]
	v_mfma_f32_16x16x32_bf16 v[90:93], v[156:159], v[182:185], v[90:93]
	v_mfma_f32_16x16x32_bf16 v[78:81], v[148:151], v[190:193], v[78:81]
	v_mfma_f32_16x16x32_bf16 v[74:77], v[156:159], v[190:193], v[74:77]
	v_mfma_f32_16x16x32_bf16 v[70:73], v[148:151], v[204:207], v[70:73]
	v_mfma_f32_16x16x32_bf16 v[66:69], v[156:159], v[204:207], v[66:69]
	v_mfma_f32_16x16x32_bf16 v[112:115], v[152:155], v[168:171], v[112:115]
	v_mfma_f32_16x16x32_bf16 v[108:111], v[160:163], v[168:171], v[108:111]
	v_mfma_f32_16x16x32_bf16 v[94:97], v[152:155], v[186:189], v[94:97]
	v_mfma_f32_16x16x32_bf16 v[90:93], v[160:163], v[186:189], v[90:93]
	v_mfma_f32_16x16x32_bf16 v[78:81], v[152:155], v[194:197], v[78:81]
	v_mfma_f32_16x16x32_bf16 v[74:77], v[160:163], v[194:197], v[74:77]
	v_mfma_f32_16x16x32_bf16 v[70:73], v[152:155], v[208:211], v[70:73]
	v_mfma_f32_16x16x32_bf16 v[66:69], v[160:163], v[208:211], v[66:69]
	s_barrier
	s_add_i32 s50, s64, s2
	v_lshl_add_u64 v[214:215], v[214:215], 0, s[28:29]
	s_mov_b32 m0, s50
	ds_read_b128 v[164:167], v199 offset:49152
	ds_read_b128 v[168:171], v199 offset:50176
	ds_read_b128 v[182:185], v199 offset:51200
	ds_read_b128 v[186:189], v199 offset:52224
	ds_read_b128 v[190:193], v199 offset:53248
	ds_read_b128 v[194:197], v199 offset:54272
	ds_read_b128 v[204:207], v199 offset:55296
	ds_read_b128 v[208:211], v199 offset:56320
	global_load_lds_dwordx4 v[214:215], off
	s_add_i32 m0, s50, 0x2000
	s_add_u32 s50, s54, 0xb0080
	v_lshl_add_u64 v[214:215], v[216:217], 0, s[28:29]
	s_addc_u32 s51, s55, 0
	s_add_i32 s54, s65, s2
	global_load_lds_dwordx4 v[214:215], off
	v_lshl_add_u64 v[214:215], s[50:51], 0, v[98:99]
	s_mov_b32 m0, s54
	s_nop 0
	global_load_lds_dwordx4 v[214:215], off
	v_lshl_add_u64 v[214:215], s[50:51], 0, v[172:173]
	s_add_i32 m0, s54, 0x2000
	s_nop 0
	global_load_lds_dwordx4 v[214:215], off
	v_lshl_add_u64 v[214:215], v[218:219], 0, s[28:29]
	s_mov_b32 m0, s12
	s_nop 0
	global_load_lds_dwordx4 v[214:215], off
	v_lshl_add_u64 v[214:215], v[220:221], 0, s[28:29]
	s_mov_b32 m0, s13
	s_nop 0
	global_load_lds_dwordx4 v[214:215], off
	s_waitcnt vmcnt(8)
	s_waitcnt lgkmcnt(0)
	s_barrier
	v_mfma_f32_16x16x32_bf16 v[62:65], v[132:135], v[164:167], v[62:65]
	v_mfma_f32_16x16x32_bf16 v[58:61], v[140:143], v[164:167], v[58:61]
	v_mfma_f32_16x16x32_bf16 v[54:57], v[132:135], v[182:185], v[54:57]
	v_mfma_f32_16x16x32_bf16 v[50:53], v[140:143], v[182:185], v[50:53]
	v_mfma_f32_16x16x32_bf16 v[38:41], v[132:135], v[190:193], v[38:41]
	v_mfma_f32_16x16x32_bf16 v[34:37], v[140:143], v[190:193], v[34:37]
	v_mfma_f32_16x16x32_bf16 v[22:25], v[132:135], v[204:207], v[22:25]
	v_mfma_f32_16x16x32_bf16 v[18:21], v[140:143], v[204:207], v[18:21]
	v_mfma_f32_16x16x32_bf16 v[62:65], v[136:139], v[168:171], v[62:65]
	v_mfma_f32_16x16x32_bf16 v[58:61], v[144:147], v[168:171], v[58:61]
	v_mfma_f32_16x16x32_bf16 v[54:57], v[136:139], v[186:189], v[54:57]
	v_mfma_f32_16x16x32_bf16 v[50:53], v[144:147], v[186:189], v[50:53]
	v_mfma_f32_16x16x32_bf16 v[38:41], v[136:139], v[194:197], v[38:41]
	v_mfma_f32_16x16x32_bf16 v[34:37], v[144:147], v[194:197], v[34:37]
	v_mfma_f32_16x16x32_bf16 v[22:25], v[136:139], v[208:211], v[22:25]
	v_mfma_f32_16x16x32_bf16 v[18:21], v[144:147], v[208:211], v[18:21]
	s_setprio 0
	s_setprio 1
	v_mfma_f32_16x16x32_bf16 v[46:49], v[148:151], v[164:167], v[46:49]
	v_mfma_f32_16x16x32_bf16 v[42:45], v[156:159], v[164:167], v[42:45]
	v_mfma_f32_16x16x32_bf16 v[30:33], v[148:151], v[182:185], v[30:33]
	v_mfma_f32_16x16x32_bf16 v[26:29], v[156:159], v[182:185], v[26:29]
	v_mfma_f32_16x16x32_bf16 v[14:17], v[148:151], v[190:193], v[14:17]
	v_mfma_f32_16x16x32_bf16 v[10:13], v[156:159], v[190:193], v[10:13]
	v_mfma_f32_16x16x32_bf16 v[6:9], v[148:151], v[204:207], v[6:9]
	v_mfma_f32_16x16x32_bf16 v[2:5], v[156:159], v[204:207], v[2:5]
	v_mfma_f32_16x16x32_bf16 v[46:49], v[152:155], v[168:171], v[46:49]
	v_mfma_f32_16x16x32_bf16 v[42:45], v[160:163], v[168:171], v[42:45]
	v_mfma_f32_16x16x32_bf16 v[30:33], v[152:155], v[186:189], v[30:33]
	v_mfma_f32_16x16x32_bf16 v[26:29], v[160:163], v[186:189], v[26:29]
	v_mfma_f32_16x16x32_bf16 v[14:17], v[152:155], v[194:197], v[14:17]
	v_mfma_f32_16x16x32_bf16 v[10:13], v[160:163], v[194:197], v[10:13]
	v_mfma_f32_16x16x32_bf16 v[6:9], v[152:155], v[208:211], v[6:9]
	v_mfma_f32_16x16x32_bf16 v[2:5], v[160:163], v[208:211], v[2:5]
	s_setprio 0
	s_barrier
	s_add_u32 s61, s61, 0x100
	s_addc_u32 s62, s62, 0
	s_cmp_ge_i32 s63, s59
	s_mov_b64 s[50:51], s[52:53]
	s_mov_b32 s54, s63
	s_cbranch_scc0 .LBB0_1553
	s_and_b64 vcc, exec, s[42:43]
	s_cbranch_vccz .LBB0_1556
	s_barrier
